# all code-motion patches (ATTN swp + unit prefetch, RC1 operand prefetch, P5 row-sum cache, P3/P4/P6 epilogue pipelining, IDX/PR1/PL wait fixes) with the simplified GLOBAL grid barrier only (no XCD-loc
# baseline (speedup 1.0000x reference)
.LBB0_927:
	v_lshl_or_b32 v146, s2, 8, v182
	v_readlane_b32 s68, v238, 2
	v_lshlrev_b64 v[162:163], 2, v[146:147]
	v_readlane_b32 s82, v238, 16
	v_readlane_b32 s83, v238, 17
	v_ashrrev_i32_e32 v157, 31, v156
	v_lshlrev_b64 v[160:161], 11, v[156:157]
	v_lshl_add_u64 v[158:159], s[82:83], 0, v[162:163]
	global_load_dwordx4 v[134:137], v[158:159], off
	global_load_dwordx4 v[130:133], v[158:159], off offset:16
	global_load_dwordx4 v[240:243], v[158:159], off offset:512
	global_load_dwordx4 v[244:247], v[158:159], off offset:528
	v_or_b32_e32 v164, 16, v156
	v_lshl_add_u64 v[162:163], s[8:9], 0, v[162:163]
	v_lshl_add_u64 v[166:167], v[162:163], 0, v[160:161]
	s_mov_b64 s[36:37], 0x40000
	v_or_b32_e32 v146, 0x80, v146
	v_readlane_b32 s80, v238, 14
	v_readlane_b32 s81, v238, 15
	v_readlane_b32 s80, v238, 39
	v_readlane_b32 s81, v238, 40
	v_readlane_b32 s82, v238, 41
	v_readlane_b32 s83, v238, 42
	v_readlane_b32 s69, v238, 3
	v_readlane_b32 s70, v238, 4
	v_readlane_b32 s71, v238, 5
	v_readlane_b32 s72, v238, 6
	v_readlane_b32 s73, v238, 7
	v_readlane_b32 s74, v238, 8
	v_readlane_b32 s75, v238, 9
	v_readlane_b32 s76, v238, 10
	v_readlane_b32 s77, v238, 11
	v_readlane_b32 s78, v238, 12
	v_readlane_b32 s79, v238, 13
	s_waitcnt vmcnt(2)
	v_add_f32_e32 v126, v126, v134
	v_add_f32_e32 v127, v127, v135
	v_add_f32_e32 v128, v128, v136
	v_add_f32_e32 v129, v129, v137
	v_add_f32_e32 v122, v122, v130
	v_add_f32_e32 v123, v123, v131
	v_add_f32_e32 v124, v124, v132
	v_add_f32_e32 v125, v125, v133
	v_add_f32_e32 v114, v114, v130
	v_add_f32_e32 v115, v115, v131
	v_add_f32_e32 v116, v116, v132
	v_add_f32_e32 v117, v117, v133
	v_mul_f32_e32 v126, 0xbfb8aa3b, v126
	v_mul_f32_e32 v127, 0xbfb8aa3b, v127
	v_mul_f32_e32 v128, 0xbfb8aa3b, v128
	v_mul_f32_e32 v129, 0xbfb8aa3b, v129
	v_add_f32_e32 v118, v118, v134
	v_add_f32_e32 v119, v119, v135
	v_add_f32_e32 v120, v120, v136
	v_add_f32_e32 v121, v121, v137
	v_mul_f32_e32 v122, 0xbfb8aa3b, v122
	v_mul_f32_e32 v123, 0xbfb8aa3b, v123
	v_mul_f32_e32 v124, 0xbfb8aa3b, v124
	v_mul_f32_e32 v125, 0xbfb8aa3b, v125
	v_mul_f32_e32 v114, 0xbfb8aa3b, v114
	v_mul_f32_e32 v115, 0xbfb8aa3b, v115
	v_mul_f32_e32 v116, 0xbfb8aa3b, v116
	v_mul_f32_e32 v117, 0xbfb8aa3b, v117
	v_exp_f32_e32 v126, v126
	v_exp_f32_e32 v127, v127
	v_exp_f32_e32 v128, v128
	v_exp_f32_e32 v129, v129
	v_mul_f32_e32 v118, 0xbfb8aa3b, v118
	v_mul_f32_e32 v119, 0xbfb8aa3b, v119
	v_mul_f32_e32 v120, 0xbfb8aa3b, v120
	v_mul_f32_e32 v121, 0xbfb8aa3b, v121
	v_exp_f32_e32 v122, v122
	v_exp_f32_e32 v123, v123
	v_exp_f32_e32 v124, v124
	v_exp_f32_e32 v125, v125
	v_exp_f32_e32 v114, v114
	v_exp_f32_e32 v115, v115
	v_exp_f32_e32 v116, v116
	v_exp_f32_e32 v117, v117
	v_exp_f32_e32 v118, v118
	v_exp_f32_e32 v119, v119
	v_exp_f32_e32 v120, v120
	v_exp_f32_e32 v121, v121
	v_add_f32_e32 v126, 1.0, v126
	v_add_f32_e32 v127, 1.0, v127
	v_add_f32_e32 v128, 1.0, v128
	v_add_f32_e32 v129, 1.0, v129
	v_add_f32_e32 v122, 1.0, v122
	v_add_f32_e32 v123, 1.0, v123
	v_add_f32_e32 v124, 1.0, v124
	v_add_f32_e32 v125, 1.0, v125
	v_add_f32_e32 v170, 1.0, v114
	v_add_f32_e32 v171, 1.0, v115
	v_add_f32_e32 v172, 1.0, v116
	v_add_f32_e32 v173, 1.0, v117
	v_rcp_f32_e32 v114, v126
	v_rcp_f32_e32 v115, v127
	v_rcp_f32_e32 v116, v128
	v_rcp_f32_e32 v117, v129
	v_add_f32_e32 v110, v110, v134
	v_add_f32_e32 v157, 1.0, v118
	v_add_f32_e32 v165, 1.0, v119
	v_add_f32_e32 v168, 1.0, v120
	v_add_f32_e32 v169, 1.0, v121
	v_rcp_f32_e32 v118, v122
	v_rcp_f32_e32 v119, v123
	v_rcp_f32_e32 v120, v124
	v_rcp_f32_e32 v121, v125
	v_mul_f32_e32 v110, 0xbfb8aa3b, v110
	v_add_f32_e32 v111, v111, v135
	v_rcp_f32_e32 v122, v157
	v_rcp_f32_e32 v123, v165
	v_rcp_f32_e32 v124, v168
	v_rcp_f32_e32 v125, v169
	v_exp_f32_e32 v110, v110
	v_mul_f32_e32 v111, 0xbfb8aa3b, v111
	v_rcp_f32_e32 v126, v170
	v_rcp_f32_e32 v127, v171
	v_rcp_f32_e32 v128, v172
	v_rcp_f32_e32 v129, v173
	v_exp_f32_e32 v111, v111
	v_pk_mul_f32 v[116:117], v[116:117], s[26:27] op_sel_hi:[1,0]
	v_pk_mul_f32 v[114:115], v[114:115], s[26:27] op_sel_hi:[1,0]
	v_ashrrev_i32_e32 v165, 31, v164
	v_pk_mul_f32 v[120:121], v[120:121], s[26:27] op_sel_hi:[1,0]
	v_pk_mul_f32 v[118:119], v[118:119], s[26:27] op_sel_hi:[1,0]
	global_store_dwordx4 v[166:167], v[114:117], off
	global_store_dwordx4 v[166:167], v[118:121], off offset:16
	v_add_f32_e32 v110, 1.0, v110
	v_lshlrev_b64 v[114:115], 11, v[164:165]
	v_pk_mul_f32 v[118:119], v[124:125], s[26:27] op_sel_hi:[1,0]
	v_pk_mul_f32 v[116:117], v[122:123], s[26:27] op_sel_hi:[1,0]
	v_lshl_add_u64 v[124:125], v[162:163], 0, v[114:115]
	v_add_f32_e32 v106, v106, v130
	v_add_f32_e32 v107, v107, v131
	v_add_f32_e32 v108, v108, v132
	v_pk_mul_f32 v[122:123], v[128:129], s[26:27] op_sel_hi:[1,0]
	v_pk_mul_f32 v[120:121], v[126:127], s[26:27] op_sel_hi:[1,0]
	global_store_dwordx4 v[124:125], v[116:119], off
	global_store_dwordx4 v[124:125], v[120:123], off offset:16
	v_add_f32_e32 v112, v112, v136
	v_rcp_f32_e32 v116, v110
	v_add_f32_e32 v110, 1.0, v111
	v_add_f32_e32 v111, v113, v137
	v_mul_f32_e32 v106, 0xbfb8aa3b, v106
	v_mul_f32_e32 v107, 0xbfb8aa3b, v107
	v_mul_f32_e32 v108, 0xbfb8aa3b, v108
	v_add_f32_e32 v109, v109, v133
	v_mul_f32_e32 v112, 0xbfb8aa3b, v112
	v_mul_f32_e32 v111, 0xbfb8aa3b, v111
	v_exp_f32_e32 v106, v106
	v_exp_f32_e32 v107, v107
	v_exp_f32_e32 v108, v108
	v_mul_f32_e32 v109, 0xbfb8aa3b, v109
	v_exp_f32_e32 v112, v112
	v_exp_f32_e32 v111, v111
	v_exp_f32_e32 v109, v109
	v_add_f32_e32 v106, 1.0, v106
	v_add_f32_e32 v107, 1.0, v107
	v_add_f32_e32 v108, 1.0, v108
	v_add_f32_e32 v102, v102, v134
	v_rcp_f32_e32 v117, v110
	v_add_f32_e32 v110, 1.0, v112
	v_add_f32_e32 v111, 1.0, v111
	v_rcp_f32_e32 v106, v106
	v_rcp_f32_e32 v112, v108
	v_add_f32_e32 v108, 1.0, v109
	v_rcp_f32_e32 v107, v107
	v_mul_f32_e32 v102, 0xbfb8aa3b, v102
	v_add_f32_e32 v103, v103, v135
	v_rcp_f32_e32 v110, v110
	v_rcp_f32_e32 v111, v111
	v_rcp_f32_e32 v113, v108
	v_exp_f32_e32 v102, v102
	v_mul_f32_e32 v103, 0xbfb8aa3b, v103
	v_or_b32_e32 v120, 32, v156
	v_exp_f32_e32 v103, v103
	v_ashrrev_i32_e32 v121, 31, v120
	v_pk_mul_f32 v[108:109], v[116:117], s[26:27] op_sel_hi:[1,0]
	v_pk_mul_f32 v[116:117], v[106:107], s[26:27] op_sel_hi:[1,0]
	v_lshlrev_b64 v[106:107], 11, v[120:121]
	v_pk_mul_f32 v[110:111], v[110:111], s[26:27] op_sel_hi:[1,0]
	v_pk_mul_f32 v[118:119], v[112:113], s[26:27] op_sel_hi:[1,0]
	v_lshl_add_u64 v[112:113], v[162:163], 0, v[106:107]
	v_add_f32_e32 v102, 1.0, v102
	v_add_f32_e32 v98, v98, v130
	v_add_f32_e32 v99, v99, v131
	v_add_f32_e32 v100, v100, v132
	global_store_dwordx4 v[112:113], v[108:111], off
	global_store_dwordx4 v[112:113], v[116:119], off offset:16
	v_add_f32_e32 v104, v104, v136
	v_rcp_f32_e32 v108, v102
	v_add_f32_e32 v102, 1.0, v103
	v_add_f32_e32 v103, v105, v137
	v_mul_f32_e32 v98, 0xbfb8aa3b, v98
	v_mul_f32_e32 v99, 0xbfb8aa3b, v99
	v_mul_f32_e32 v100, 0xbfb8aa3b, v100
	v_add_f32_e32 v101, v101, v133
	v_mul_f32_e32 v104, 0xbfb8aa3b, v104
	v_mul_f32_e32 v103, 0xbfb8aa3b, v103
	v_exp_f32_e32 v98, v98
	v_exp_f32_e32 v99, v99
	v_exp_f32_e32 v100, v100
	v_mul_f32_e32 v101, 0xbfb8aa3b, v101
	v_exp_f32_e32 v104, v104
	v_exp_f32_e32 v103, v103
	v_exp_f32_e32 v101, v101
	v_add_f32_e32 v98, 1.0, v98
	v_add_f32_e32 v99, 1.0, v99
	v_add_f32_e32 v100, 1.0, v100
	v_add_f32_e32 v94, v94, v134
	v_rcp_f32_e32 v109, v102
	v_add_f32_e32 v102, 1.0, v104
	v_add_f32_e32 v103, 1.0, v103
	v_rcp_f32_e32 v98, v98
	v_rcp_f32_e32 v104, v100
	v_add_f32_e32 v100, 1.0, v101
	v_rcp_f32_e32 v99, v99
	v_mul_f32_e32 v94, 0xbfb8aa3b, v94
	v_add_f32_e32 v95, v95, v135
	v_rcp_f32_e32 v102, v102
	v_rcp_f32_e32 v103, v103
	v_rcp_f32_e32 v105, v100
	v_exp_f32_e32 v94, v94
	v_mul_f32_e32 v95, 0xbfb8aa3b, v95
	v_or_b32_e32 v112, 48, v156
	v_exp_f32_e32 v95, v95
	v_ashrrev_i32_e32 v113, 31, v112
	v_pk_mul_f32 v[100:101], v[108:109], s[26:27] op_sel_hi:[1,0]
	v_pk_mul_f32 v[108:109], v[98:99], s[26:27] op_sel_hi:[1,0]
	v_lshlrev_b64 v[98:99], 11, v[112:113]
	v_pk_mul_f32 v[102:103], v[102:103], s[26:27] op_sel_hi:[1,0]
	v_pk_mul_f32 v[110:111], v[104:105], s[26:27] op_sel_hi:[1,0]
	v_lshl_add_u64 v[104:105], v[162:163], 0, v[98:99]
	v_add_f32_e32 v94, 1.0, v94
	v_add_f32_e32 v90, v90, v130
	v_add_f32_e32 v91, v91, v131
	v_add_f32_e32 v92, v92, v132
	global_store_dwordx4 v[104:105], v[100:103], off
	global_store_dwordx4 v[104:105], v[108:111], off offset:16
	v_add_f32_e32 v96, v96, v136
	v_rcp_f32_e32 v100, v94
	v_add_f32_e32 v94, 1.0, v95
	v_add_f32_e32 v95, v97, v137
	v_mul_f32_e32 v90, 0xbfb8aa3b, v90
	v_mul_f32_e32 v91, 0xbfb8aa3b, v91
	v_mul_f32_e32 v92, 0xbfb8aa3b, v92
	v_add_f32_e32 v93, v93, v133
	v_mul_f32_e32 v96, 0xbfb8aa3b, v96
	v_mul_f32_e32 v95, 0xbfb8aa3b, v95
	v_exp_f32_e32 v90, v90
	v_exp_f32_e32 v91, v91
	v_exp_f32_e32 v92, v92
	v_mul_f32_e32 v93, 0xbfb8aa3b, v93
	v_exp_f32_e32 v96, v96
	v_exp_f32_e32 v95, v95
	v_exp_f32_e32 v93, v93
	v_add_f32_e32 v90, 1.0, v90
	v_add_f32_e32 v91, 1.0, v91
	v_add_f32_e32 v92, 1.0, v92
	v_add_f32_e32 v86, v86, v134
	v_rcp_f32_e32 v101, v94
	v_add_f32_e32 v94, 1.0, v96
	v_add_f32_e32 v95, 1.0, v95
	v_rcp_f32_e32 v90, v90
	v_rcp_f32_e32 v96, v92
	v_add_f32_e32 v92, 1.0, v93
	v_rcp_f32_e32 v91, v91
	v_mul_f32_e32 v86, 0xbfb8aa3b, v86
	v_add_f32_e32 v87, v87, v135
	v_rcp_f32_e32 v94, v94
	v_rcp_f32_e32 v95, v95
	v_rcp_f32_e32 v97, v92
	v_exp_f32_e32 v86, v86
	v_mul_f32_e32 v87, 0xbfb8aa3b, v87
	v_exp_f32_e32 v87, v87
	v_pk_mul_f32 v[92:93], v[100:101], s[26:27] op_sel_hi:[1,0]
	v_pk_mul_f32 v[100:101], v[90:91], s[26:27] op_sel_hi:[1,0]
	v_lshl_add_u64 v[90:91], v[160:161], 0, s[36:37]
	v_pk_mul_f32 v[94:95], v[94:95], s[26:27] op_sel_hi:[1,0]
	v_pk_mul_f32 v[102:103], v[96:97], s[26:27] op_sel_hi:[1,0]
	v_lshl_add_u64 v[96:97], v[162:163], 0, v[90:91]
	v_add_f32_e32 v86, 1.0, v86
	v_add_f32_e32 v82, v82, v130
	v_add_f32_e32 v83, v83, v131
	v_add_f32_e32 v84, v84, v132
	global_store_dwordx4 v[96:97], v[92:95], off
	global_store_dwordx4 v[96:97], v[100:103], off offset:16
	v_add_f32_e32 v88, v88, v136
	v_rcp_f32_e32 v92, v86
	v_add_f32_e32 v86, 1.0, v87
	v_add_f32_e32 v87, v89, v137
	v_mul_f32_e32 v82, 0xbfb8aa3b, v82
	v_mul_f32_e32 v83, 0xbfb8aa3b, v83
	v_mul_f32_e32 v84, 0xbfb8aa3b, v84
	v_add_f32_e32 v85, v85, v133
	v_mul_f32_e32 v88, 0xbfb8aa3b, v88
	v_mul_f32_e32 v87, 0xbfb8aa3b, v87
	v_exp_f32_e32 v82, v82
	v_exp_f32_e32 v83, v83
	v_exp_f32_e32 v84, v84
	v_mul_f32_e32 v85, 0xbfb8aa3b, v85
	v_exp_f32_e32 v88, v88
	v_exp_f32_e32 v87, v87
	v_exp_f32_e32 v85, v85
	v_add_f32_e32 v82, 1.0, v82
	v_add_f32_e32 v83, 1.0, v83
	v_add_f32_e32 v84, 1.0, v84
	v_add_f32_e32 v78, v78, v134
	v_rcp_f32_e32 v93, v86
	v_add_f32_e32 v86, 1.0, v88
	v_add_f32_e32 v87, 1.0, v87
	v_rcp_f32_e32 v82, v82
	v_rcp_f32_e32 v88, v84
	v_add_f32_e32 v84, 1.0, v85
	v_rcp_f32_e32 v83, v83
	v_mul_f32_e32 v78, 0xbfb8aa3b, v78
	v_add_f32_e32 v79, v79, v135
	v_rcp_f32_e32 v86, v86
	v_rcp_f32_e32 v87, v87
	v_rcp_f32_e32 v89, v84
	v_exp_f32_e32 v78, v78
	v_mul_f32_e32 v79, 0xbfb8aa3b, v79
	v_exp_f32_e32 v79, v79
	s_mov_b64 s[36:37], 0x48000
	v_pk_mul_f32 v[84:85], v[92:93], s[26:27] op_sel_hi:[1,0]
	v_pk_mul_f32 v[92:93], v[82:83], s[26:27] op_sel_hi:[1,0]
	v_lshl_add_u64 v[82:83], v[160:161], 0, s[36:37]
	v_pk_mul_f32 v[86:87], v[86:87], s[26:27] op_sel_hi:[1,0]
	v_pk_mul_f32 v[94:95], v[88:89], s[26:27] op_sel_hi:[1,0]
	v_lshl_add_u64 v[88:89], v[162:163], 0, v[82:83]
	v_add_f32_e32 v78, 1.0, v78
	v_add_f32_e32 v74, v74, v130
	v_add_f32_e32 v75, v75, v131
	v_add_f32_e32 v76, v76, v132
	global_store_dwordx4 v[88:89], v[84:87], off
	global_store_dwordx4 v[88:89], v[92:95], off offset:16
	v_add_f32_e32 v80, v80, v136
	v_rcp_f32_e32 v84, v78
	v_add_f32_e32 v78, 1.0, v79
	v_add_f32_e32 v79, v81, v137
	v_mul_f32_e32 v74, 0xbfb8aa3b, v74
	v_mul_f32_e32 v75, 0xbfb8aa3b, v75
	v_mul_f32_e32 v76, 0xbfb8aa3b, v76
	v_add_f32_e32 v77, v77, v133
	v_mul_f32_e32 v80, 0xbfb8aa3b, v80
	v_mul_f32_e32 v79, 0xbfb8aa3b, v79
	v_exp_f32_e32 v74, v74
	v_exp_f32_e32 v75, v75
	v_exp_f32_e32 v76, v76
	v_mul_f32_e32 v77, 0xbfb8aa3b, v77
	v_exp_f32_e32 v80, v80
	v_exp_f32_e32 v79, v79
	v_exp_f32_e32 v77, v77
	v_add_f32_e32 v74, 1.0, v74
	v_add_f32_e32 v75, 1.0, v75
	v_add_f32_e32 v76, 1.0, v76
	v_add_f32_e32 v62, v62, v130
	v_rcp_f32_e32 v85, v78
	v_add_f32_e32 v78, 1.0, v80
	v_add_f32_e32 v79, 1.0, v79
	v_rcp_f32_e32 v74, v74
	v_rcp_f32_e32 v80, v76
	v_add_f32_e32 v76, 1.0, v77
	v_rcp_f32_e32 v75, v75
	v_mul_f32_e32 v62, 0xbfb8aa3b, v62
	v_rcp_f32_e32 v78, v78
	v_rcp_f32_e32 v79, v79
	v_rcp_f32_e32 v81, v76
	v_exp_f32_e32 v62, v62
	v_pk_mul_f32 v[76:77], v[84:85], s[26:27] op_sel_hi:[1,0]
	v_pk_mul_f32 v[84:85], v[74:75], s[26:27] op_sel_hi:[1,0]
	v_lshl_add_u64 v[74:75], v[160:161], 0, s[28:29]
	v_pk_mul_f32 v[78:79], v[78:79], s[26:27] op_sel_hi:[1,0]
	v_pk_mul_f32 v[86:87], v[80:81], s[26:27] op_sel_hi:[1,0]
	v_lshl_add_u64 v[80:81], v[162:163], 0, v[74:75]
	v_add_f32_e32 v62, 1.0, v62
	v_add_f32_e32 v70, v70, v134
	global_store_dwordx4 v[80:81], v[76:79], off
	global_store_dwordx4 v[80:81], v[84:87], off offset:16
	v_add_f32_e32 v71, v71, v135
	v_rcp_f32_e32 v76, v62
	v_add_f32_e32 v62, v63, v131
	v_add_f32_e32 v63, v64, v132
	v_mul_f32_e32 v70, 0xbfb8aa3b, v70
	v_mul_f32_e32 v71, 0xbfb8aa3b, v71
	v_add_f32_e32 v72, v72, v136
	v_add_f32_e32 v73, v73, v137
	v_mul_f32_e32 v62, 0xbfb8aa3b, v62
	v_mul_f32_e32 v63, 0xbfb8aa3b, v63
	v_add_f32_e32 v64, v65, v133
	v_exp_f32_e32 v70, v70
	v_exp_f32_e32 v71, v71
	v_mul_f32_e32 v72, 0xbfb8aa3b, v72
	v_mul_f32_e32 v73, 0xbfb8aa3b, v73
	v_exp_f32_e32 v62, v62
	v_exp_f32_e32 v63, v63
	v_mul_f32_e32 v64, 0xbfb8aa3b, v64
	v_exp_f32_e32 v72, v72
	v_exp_f32_e32 v73, v73
	v_exp_f32_e32 v64, v64
	v_add_f32_e32 v70, 1.0, v70
	v_add_f32_e32 v71, 1.0, v71
	v_add_f32_e32 v62, 1.0, v62
	v_add_f32_e32 v63, 1.0, v63
	v_rcp_f32_e32 v70, v70
	v_rcp_f32_e32 v71, v71
	v_add_f32_e32 v72, 1.0, v72
	v_add_f32_e32 v73, 1.0, v73
	v_rcp_f32_e32 v78, v63
	v_add_f32_e32 v63, 1.0, v64
	v_rcp_f32_e32 v77, v62
	v_rcp_f32_e32 v72, v72
	v_rcp_f32_e32 v73, v73
	v_rcp_f32_e32 v79, v63
	v_pk_mul_f32 v[62:63], v[70:71], s[26:27] op_sel_hi:[1,0]
	v_pk_mul_f32 v[70:71], v[76:77], s[26:27] op_sel_hi:[1,0]
	v_lshl_add_u64 v[76:77], v[160:161], 0, s[30:31]
	v_pk_mul_f32 v[64:65], v[72:73], s[26:27] op_sel_hi:[1,0]
	v_pk_mul_f32 v[72:73], v[78:79], s[26:27] op_sel_hi:[1,0]
	v_lshl_add_u64 v[78:79], v[162:163], 0, v[76:77]
	global_store_dwordx4 v[78:79], v[62:65], off
	global_store_dwordx4 v[78:79], v[70:73], off offset:16
	s_nop 3
	s_waitcnt vmcnt(16)
	v_mov_b64_e32 v[70:71], v[240:241]
	v_mov_b64_e32 v[72:73], v[242:243]
	v_mov_b64_e32 v[62:63], v[244:245]
	v_mov_b64_e32 v[64:65], v[246:247]
	v_add_f32_e32 v66, v66, v70
	v_add_f32_e32 v58, v58, v62
	v_add_f32_e32 v59, v59, v63
	v_add_f32_e32 v60, v60, v64
	v_add_f32_e32 v61, v61, v65
	v_add_f32_e32 v67, v67, v71
	v_add_f32_e32 v68, v68, v72
	v_add_f32_e32 v69, v69, v73
	v_mul_f32_e32 v58, 0xbfb8aa3b, v58
	v_mul_f32_e32 v59, 0xbfb8aa3b, v59
	v_mul_f32_e32 v60, 0xbfb8aa3b, v60
	v_mul_f32_e32 v61, 0xbfb8aa3b, v61
	v_mul_f32_e32 v66, 0xbfb8aa3b, v66
	v_mul_f32_e32 v67, 0xbfb8aa3b, v67
	v_mul_f32_e32 v68, 0xbfb8aa3b, v68
	v_mul_f32_e32 v69, 0xbfb8aa3b, v69
	v_exp_f32_e32 v58, v58
	v_exp_f32_e32 v59, v59
	v_exp_f32_e32 v60, v60
	v_exp_f32_e32 v61, v61
	v_exp_f32_e32 v66, v66
	v_exp_f32_e32 v67, v67
	v_exp_f32_e32 v68, v68
	v_exp_f32_e32 v69, v69
	v_add_f32_e32 v58, 1.0, v58
	v_add_f32_e32 v59, 1.0, v59
	v_add_f32_e32 v60, 1.0, v60
	v_add_f32_e32 v61, 1.0, v61
	v_add_f32_e32 v50, v50, v62
	v_add_f32_e32 v66, 1.0, v66
	v_add_f32_e32 v67, 1.0, v67
	v_add_f32_e32 v68, 1.0, v68
	v_add_f32_e32 v69, 1.0, v69
	v_rcp_f32_e32 v58, v58
	v_rcp_f32_e32 v60, v60
	v_rcp_f32_e32 v61, v61
	v_rcp_f32_e32 v59, v59
	v_mul_f32_e32 v50, 0xbfb8aa3b, v50
	v_rcp_f32_e32 v66, v66
	v_rcp_f32_e32 v67, v67
	v_rcp_f32_e32 v68, v68
	v_rcp_f32_e32 v69, v69
	v_exp_f32_e32 v50, v50
	v_pk_mul_f32 v[80:81], v[60:61], s[26:27] op_sel_hi:[1,0]
	v_pk_mul_f32 v[78:79], v[58:59], s[26:27] op_sel_hi:[1,0]
	v_lshl_add_u64 v[60:61], s[8:9], 0, v[160:161]
	v_lshlrev_b64 v[58:59], 2, v[146:147]
	v_pk_mul_f32 v[68:69], v[68:69], s[26:27] op_sel_hi:[1,0]
	v_pk_mul_f32 v[66:67], v[66:67], s[26:27] op_sel_hi:[1,0]
	v_lshl_add_u64 v[60:61], v[60:61], 0, v[58:59]
	v_add_f32_e32 v50, 1.0, v50
	v_add_f32_e32 v54, v54, v70
	global_store_dwordx4 v[60:61], v[66:69], off
	global_store_dwordx4 v[60:61], v[78:81], off offset:16
	v_add_f32_e32 v55, v55, v71
	v_rcp_f32_e32 v60, v50
	v_add_f32_e32 v50, v51, v63
	v_mul_f32_e32 v54, 0xbfb8aa3b, v54
	v_mul_f32_e32 v55, 0xbfb8aa3b, v55
	v_add_f32_e32 v56, v56, v72
	v_add_f32_e32 v57, v57, v73
	v_mul_f32_e32 v50, 0xbfb8aa3b, v50
	v_add_f32_e32 v51, v52, v64
	v_exp_f32_e32 v54, v54
	v_exp_f32_e32 v55, v55
	v_mul_f32_e32 v56, 0xbfb8aa3b, v56
	v_mul_f32_e32 v57, 0xbfb8aa3b, v57
	v_exp_f32_e32 v50, v50
	v_mul_f32_e32 v51, 0xbfb8aa3b, v51
	v_add_f32_e32 v52, v53, v65
	v_exp_f32_e32 v56, v56
	v_exp_f32_e32 v57, v57
	v_exp_f32_e32 v51, v51
	v_mul_f32_e32 v52, 0xbfb8aa3b, v52
	v_exp_f32_e32 v52, v52
	v_add_f32_e32 v54, 1.0, v54
	v_add_f32_e32 v55, 1.0, v55
	v_add_f32_e32 v50, 1.0, v50
	v_add_f32_e32 v42, v42, v62
	v_rcp_f32_e32 v54, v54
	v_rcp_f32_e32 v55, v55
	v_add_f32_e32 v56, 1.0, v56
	v_add_f32_e32 v57, 1.0, v57
	v_add_f32_e32 v51, 1.0, v51
	v_rcp_f32_e32 v61, v50
	v_mul_f32_e32 v42, 0xbfb8aa3b, v42
	v_rcp_f32_e32 v56, v56
	v_rcp_f32_e32 v57, v57
	v_rcp_f32_e32 v66, v51
	v_add_f32_e32 v51, 1.0, v52
	v_exp_f32_e32 v42, v42
	v_rcp_f32_e32 v67, v51
	v_pk_mul_f32 v[50:51], v[54:55], s[26:27] op_sel_hi:[1,0]
	v_pk_mul_f32 v[54:55], v[60:61], s[26:27] op_sel_hi:[1,0]
	v_lshl_add_u64 v[60:61], s[8:9], 0, v[114:115]
	v_pk_mul_f32 v[52:53], v[56:57], s[26:27] op_sel_hi:[1,0]
	v_lshl_add_u64 v[60:61], v[60:61], 0, v[58:59]
	v_add_f32_e32 v42, 1.0, v42
	v_pk_mul_f32 v[56:57], v[66:67], s[26:27] op_sel_hi:[1,0]
	v_add_f32_e32 v46, v46, v70
	global_store_dwordx4 v[60:61], v[50:53], off
	global_store_dwordx4 v[60:61], v[54:57], off offset:16
	v_add_f32_e32 v47, v47, v71
	v_rcp_f32_e32 v50, v42
	v_add_f32_e32 v42, v43, v63
	v_mul_f32_e32 v46, 0xbfb8aa3b, v46
	v_mul_f32_e32 v47, 0xbfb8aa3b, v47
	v_add_f32_e32 v48, v48, v72
	v_add_f32_e32 v49, v49, v73
	v_mul_f32_e32 v42, 0xbfb8aa3b, v42
	v_add_f32_e32 v43, v44, v64
	v_exp_f32_e32 v46, v46
	v_exp_f32_e32 v47, v47
	v_mul_f32_e32 v48, 0xbfb8aa3b, v48
	v_mul_f32_e32 v49, 0xbfb8aa3b, v49
	v_exp_f32_e32 v42, v42
	v_mul_f32_e32 v43, 0xbfb8aa3b, v43
	v_add_f32_e32 v44, v45, v65
	v_exp_f32_e32 v48, v48
	v_exp_f32_e32 v49, v49
	v_exp_f32_e32 v43, v43
	v_mul_f32_e32 v44, 0xbfb8aa3b, v44
	v_exp_f32_e32 v44, v44
	v_add_f32_e32 v46, 1.0, v46
	v_add_f32_e32 v47, 1.0, v47
	v_add_f32_e32 v42, 1.0, v42
	v_add_f32_e32 v34, v34, v62
	v_rcp_f32_e32 v46, v46
	v_rcp_f32_e32 v47, v47
	v_add_f32_e32 v48, 1.0, v48
	v_add_f32_e32 v49, 1.0, v49
	v_add_f32_e32 v43, 1.0, v43
	v_rcp_f32_e32 v51, v42
	v_mul_f32_e32 v34, 0xbfb8aa3b, v34
	v_rcp_f32_e32 v48, v48
	v_rcp_f32_e32 v49, v49
	v_rcp_f32_e32 v52, v43
	v_add_f32_e32 v43, 1.0, v44
	v_exp_f32_e32 v34, v34
	v_rcp_f32_e32 v53, v43
	v_pk_mul_f32 v[42:43], v[46:47], s[26:27] op_sel_hi:[1,0]
	v_pk_mul_f32 v[46:47], v[50:51], s[26:27] op_sel_hi:[1,0]
	v_lshl_add_u64 v[50:51], s[8:9], 0, v[106:107]
	v_pk_mul_f32 v[44:45], v[48:49], s[26:27] op_sel_hi:[1,0]
	v_lshl_add_u64 v[50:51], v[50:51], 0, v[58:59]
	v_add_f32_e32 v34, 1.0, v34
	v_pk_mul_f32 v[48:49], v[52:53], s[26:27] op_sel_hi:[1,0]
	v_add_f32_e32 v38, v38, v70
	global_store_dwordx4 v[50:51], v[42:45], off
	global_store_dwordx4 v[50:51], v[46:49], off offset:16
	v_add_f32_e32 v39, v39, v71
	v_rcp_f32_e32 v42, v34
	v_add_f32_e32 v34, v35, v63
	v_mul_f32_e32 v38, 0xbfb8aa3b, v38
	v_mul_f32_e32 v39, 0xbfb8aa3b, v39
	v_add_f32_e32 v40, v40, v72
	v_add_f32_e32 v41, v41, v73
	v_mul_f32_e32 v34, 0xbfb8aa3b, v34
	v_add_f32_e32 v35, v36, v64
	v_exp_f32_e32 v38, v38
	v_exp_f32_e32 v39, v39
	v_mul_f32_e32 v40, 0xbfb8aa3b, v40
	v_mul_f32_e32 v41, 0xbfb8aa3b, v41
	v_exp_f32_e32 v34, v34
	v_mul_f32_e32 v35, 0xbfb8aa3b, v35
	v_add_f32_e32 v36, v37, v65
	v_exp_f32_e32 v40, v40
	v_exp_f32_e32 v41, v41
	v_exp_f32_e32 v35, v35
	v_mul_f32_e32 v36, 0xbfb8aa3b, v36
	v_exp_f32_e32 v36, v36
	v_add_f32_e32 v38, 1.0, v38
	v_add_f32_e32 v39, 1.0, v39
	v_add_f32_e32 v34, 1.0, v34
	v_add_f32_e32 v26, v26, v62
	v_rcp_f32_e32 v38, v38
	v_rcp_f32_e32 v39, v39
	v_add_f32_e32 v40, 1.0, v40
	v_add_f32_e32 v41, 1.0, v41
	v_add_f32_e32 v35, 1.0, v35
	v_rcp_f32_e32 v43, v34
	v_mul_f32_e32 v26, 0xbfb8aa3b, v26
	v_rcp_f32_e32 v40, v40
	v_rcp_f32_e32 v41, v41
	v_rcp_f32_e32 v44, v35
	v_add_f32_e32 v35, 1.0, v36
	v_exp_f32_e32 v26, v26
	v_rcp_f32_e32 v45, v35
	v_pk_mul_f32 v[34:35], v[38:39], s[26:27] op_sel_hi:[1,0]
	v_pk_mul_f32 v[38:39], v[42:43], s[26:27] op_sel_hi:[1,0]
	v_lshl_add_u64 v[42:43], s[8:9], 0, v[98:99]
	v_pk_mul_f32 v[36:37], v[40:41], s[26:27] op_sel_hi:[1,0]
	v_lshl_add_u64 v[42:43], v[42:43], 0, v[58:59]
	v_add_f32_e32 v26, 1.0, v26
	v_pk_mul_f32 v[40:41], v[44:45], s[26:27] op_sel_hi:[1,0]
	v_add_f32_e32 v30, v30, v70
	global_store_dwordx4 v[42:43], v[34:37], off
	global_store_dwordx4 v[42:43], v[38:41], off offset:16
	v_add_f32_e32 v31, v31, v71
	v_rcp_f32_e32 v34, v26
	v_add_f32_e32 v26, v27, v63
	v_mul_f32_e32 v30, 0xbfb8aa3b, v30
	v_mul_f32_e32 v31, 0xbfb8aa3b, v31
	v_add_f32_e32 v32, v32, v72
	v_add_f32_e32 v33, v33, v73
	v_mul_f32_e32 v26, 0xbfb8aa3b, v26
	v_add_f32_e32 v27, v28, v64
	v_exp_f32_e32 v30, v30
	v_exp_f32_e32 v31, v31
	v_mul_f32_e32 v32, 0xbfb8aa3b, v32
	v_mul_f32_e32 v33, 0xbfb8aa3b, v33
	v_exp_f32_e32 v26, v26
	v_mul_f32_e32 v27, 0xbfb8aa3b, v27
	v_add_f32_e32 v28, v29, v65
	v_exp_f32_e32 v32, v32
	v_exp_f32_e32 v33, v33
	v_exp_f32_e32 v27, v27
	v_mul_f32_e32 v28, 0xbfb8aa3b, v28
	v_exp_f32_e32 v28, v28
	v_add_f32_e32 v30, 1.0, v30
	v_add_f32_e32 v31, 1.0, v31
	v_add_f32_e32 v26, 1.0, v26
	v_add_f32_e32 v18, v18, v62
	v_rcp_f32_e32 v30, v30
	v_rcp_f32_e32 v31, v31
	v_add_f32_e32 v32, 1.0, v32
	v_add_f32_e32 v33, 1.0, v33
	v_add_f32_e32 v27, 1.0, v27
	v_rcp_f32_e32 v35, v26
	v_mul_f32_e32 v18, 0xbfb8aa3b, v18
	v_rcp_f32_e32 v32, v32
	v_rcp_f32_e32 v33, v33
	v_rcp_f32_e32 v36, v27
	v_add_f32_e32 v27, 1.0, v28
	v_exp_f32_e32 v18, v18
	v_rcp_f32_e32 v37, v27
	v_pk_mul_f32 v[26:27], v[30:31], s[26:27] op_sel_hi:[1,0]
	v_pk_mul_f32 v[30:31], v[34:35], s[26:27] op_sel_hi:[1,0]
	v_lshl_add_u64 v[34:35], s[8:9], 0, v[90:91]
	v_pk_mul_f32 v[28:29], v[32:33], s[26:27] op_sel_hi:[1,0]
	v_lshl_add_u64 v[34:35], v[34:35], 0, v[58:59]
	v_add_f32_e32 v18, 1.0, v18
	v_pk_mul_f32 v[32:33], v[36:37], s[26:27] op_sel_hi:[1,0]
	v_add_f32_e32 v22, v22, v70
	global_store_dwordx4 v[34:35], v[26:29], off
	global_store_dwordx4 v[34:35], v[30:33], off offset:16
	v_add_f32_e32 v23, v23, v71
	v_rcp_f32_e32 v26, v18
	v_add_f32_e32 v18, v19, v63
	v_mul_f32_e32 v22, 0xbfb8aa3b, v22
	v_mul_f32_e32 v23, 0xbfb8aa3b, v23
	v_add_f32_e32 v24, v24, v72
	v_add_f32_e32 v25, v25, v73
	v_mul_f32_e32 v18, 0xbfb8aa3b, v18
	v_add_f32_e32 v19, v20, v64
	v_exp_f32_e32 v22, v22
	v_exp_f32_e32 v23, v23
	v_mul_f32_e32 v24, 0xbfb8aa3b, v24
	v_mul_f32_e32 v25, 0xbfb8aa3b, v25
	v_exp_f32_e32 v18, v18
	v_mul_f32_e32 v19, 0xbfb8aa3b, v19
	v_add_f32_e32 v20, v21, v65
	v_exp_f32_e32 v24, v24
	v_exp_f32_e32 v25, v25
	v_exp_f32_e32 v19, v19
	v_mul_f32_e32 v20, 0xbfb8aa3b, v20
	v_exp_f32_e32 v20, v20
	v_add_f32_e32 v22, 1.0, v22
	v_add_f32_e32 v23, 1.0, v23
	v_add_f32_e32 v18, 1.0, v18
	v_add_f32_e32 v10, v10, v62
	v_rcp_f32_e32 v22, v22
	v_rcp_f32_e32 v23, v23
	v_add_f32_e32 v24, 1.0, v24
	v_add_f32_e32 v25, 1.0, v25
	v_add_f32_e32 v19, 1.0, v19
	v_rcp_f32_e32 v27, v18
	v_mul_f32_e32 v10, 0xbfb8aa3b, v10
	v_rcp_f32_e32 v24, v24
	v_rcp_f32_e32 v25, v25
	v_rcp_f32_e32 v28, v19
	v_add_f32_e32 v19, 1.0, v20
	v_exp_f32_e32 v10, v10
	v_rcp_f32_e32 v29, v19
	v_pk_mul_f32 v[18:19], v[22:23], s[26:27] op_sel_hi:[1,0]
	v_pk_mul_f32 v[22:23], v[26:27], s[26:27] op_sel_hi:[1,0]
	v_lshl_add_u64 v[26:27], s[8:9], 0, v[82:83]
	v_pk_mul_f32 v[20:21], v[24:25], s[26:27] op_sel_hi:[1,0]
	v_lshl_add_u64 v[26:27], v[26:27], 0, v[58:59]
	v_add_f32_e32 v10, 1.0, v10
	v_pk_mul_f32 v[24:25], v[28:29], s[26:27] op_sel_hi:[1,0]
	v_add_f32_e32 v14, v14, v70
	global_store_dwordx4 v[26:27], v[18:21], off
	global_store_dwordx4 v[26:27], v[22:25], off offset:16
	v_add_f32_e32 v15, v15, v71
	v_rcp_f32_e32 v18, v10
	v_add_f32_e32 v10, v11, v63
	v_mul_f32_e32 v14, 0xbfb8aa3b, v14
	v_mul_f32_e32 v15, 0xbfb8aa3b, v15
	v_add_f32_e32 v16, v16, v72
	v_add_f32_e32 v17, v17, v73
	v_mul_f32_e32 v10, 0xbfb8aa3b, v10
	v_add_f32_e32 v11, v12, v64
	v_exp_f32_e32 v14, v14
	v_exp_f32_e32 v15, v15
	v_mul_f32_e32 v16, 0xbfb8aa3b, v16
	v_mul_f32_e32 v17, 0xbfb8aa3b, v17
	v_exp_f32_e32 v10, v10
	v_mul_f32_e32 v11, 0xbfb8aa3b, v11
	v_add_f32_e32 v12, v13, v65
	v_exp_f32_e32 v16, v16
	v_exp_f32_e32 v17, v17
	v_exp_f32_e32 v11, v11
	v_mul_f32_e32 v12, 0xbfb8aa3b, v12
	v_exp_f32_e32 v12, v12
	v_add_f32_e32 v14, 1.0, v14
	v_add_f32_e32 v15, 1.0, v15
	v_add_f32_e32 v10, 1.0, v10
	v_add_f32_e32 v2, v2, v62
	v_rcp_f32_e32 v14, v14
	v_rcp_f32_e32 v15, v15
	v_add_f32_e32 v16, 1.0, v16
	v_add_f32_e32 v17, 1.0, v17
	v_add_f32_e32 v11, 1.0, v11
	v_rcp_f32_e32 v19, v10
	v_mul_f32_e32 v2, 0xbfb8aa3b, v2
	v_rcp_f32_e32 v16, v16
	v_rcp_f32_e32 v17, v17
	v_rcp_f32_e32 v20, v11
	v_add_f32_e32 v11, 1.0, v12
	v_exp_f32_e32 v2, v2
	v_rcp_f32_e32 v21, v11
	v_pk_mul_f32 v[10:11], v[14:15], s[26:27] op_sel_hi:[1,0]
	v_pk_mul_f32 v[14:15], v[18:19], s[26:27] op_sel_hi:[1,0]
	v_lshl_add_u64 v[18:19], s[8:9], 0, v[74:75]
	v_pk_mul_f32 v[12:13], v[16:17], s[26:27] op_sel_hi:[1,0]
	v_lshl_add_u64 v[18:19], v[18:19], 0, v[58:59]
	v_add_f32_e32 v2, 1.0, v2
	v_pk_mul_f32 v[16:17], v[20:21], s[26:27] op_sel_hi:[1,0]
	v_add_f32_e32 v6, v6, v70
	global_store_dwordx4 v[18:19], v[10:13], off
	global_store_dwordx4 v[18:19], v[14:17], off offset:16
	v_add_f32_e32 v7, v7, v71
	v_rcp_f32_e32 v10, v2
	v_add_f32_e32 v2, v3, v63
	v_mul_f32_e32 v6, 0xbfb8aa3b, v6
	v_mul_f32_e32 v7, 0xbfb8aa3b, v7
	v_add_f32_e32 v8, v8, v72
	v_add_f32_e32 v9, v9, v73
	v_mul_f32_e32 v2, 0xbfb8aa3b, v2
	v_add_f32_e32 v3, v4, v64
	v_exp_f32_e32 v6, v6
	v_exp_f32_e32 v7, v7
	v_mul_f32_e32 v8, 0xbfb8aa3b, v8
	v_mul_f32_e32 v9, 0xbfb8aa3b, v9
	v_exp_f32_e32 v2, v2
	v_mul_f32_e32 v3, 0xbfb8aa3b, v3
	v_add_f32_e32 v4, v5, v65
	v_exp_f32_e32 v8, v8
	v_exp_f32_e32 v9, v9
	v_exp_f32_e32 v3, v3
	v_mul_f32_e32 v4, 0xbfb8aa3b, v4
	v_exp_f32_e32 v4, v4
	v_add_f32_e32 v6, 1.0, v6
	v_add_f32_e32 v7, 1.0, v7
	v_add_f32_e32 v2, 1.0, v2
	v_rcp_f32_e32 v6, v6
	v_rcp_f32_e32 v7, v7
	v_add_f32_e32 v8, 1.0, v8
	v_add_f32_e32 v9, 1.0, v9
	v_add_f32_e32 v3, 1.0, v3
	v_rcp_f32_e32 v11, v2
	v_rcp_f32_e32 v8, v8
	v_rcp_f32_e32 v9, v9
	v_rcp_f32_e32 v12, v3
	v_add_f32_e32 v3, 1.0, v4
	v_rcp_f32_e32 v13, v3
	v_pk_mul_f32 v[2:3], v[6:7], s[26:27] op_sel_hi:[1,0]
	v_pk_mul_f32 v[6:7], v[10:11], s[26:27] op_sel_hi:[1,0]
	v_lshl_add_u64 v[10:11], s[8:9], 0, v[76:77]
	v_pk_mul_f32 v[4:5], v[8:9], s[26:27] op_sel_hi:[1,0]
	v_lshl_add_u64 v[10:11], v[10:11], 0, v[58:59]
	v_pk_mul_f32 v[8:9], v[12:13], s[26:27] op_sel_hi:[1,0]
	global_store_dwordx4 v[10:11], v[2:5], off
	global_store_dwordx4 v[10:11], v[6:9], off offset:16
	s_and_b64 vcc, exec, s[4:5]
	s_mov_b64 s[4:5], -1
	s_cbranch_vccnz .LBB0_915
	s_branch .LBB0_935

.LBB0_931:
	s_andn2_b64 vcc, exec, s[36:37]
	s_cbranch_vccnz .LBB0_933
	s_mov_b64 s[36:37], s[80:81]
	s_mov_b64 s[38:39], s[82:83]
	v_readlane_b32 s68, v238, 20
	v_lshlrev_b32_e32 v186, 2, v130
	v_readlane_b32 s70, v238, 22
	v_readlane_b32 s71, v238, 23
	s_nop 4
	global_load_dwordx4 v[134:137], v186, s[70:71]
	global_load_dwordx4 v[130:133], v186, s[70:71] offset:16
	global_load_dwordx4 v[240:243], v186, s[70:71] offset:512
	global_load_dwordx4 v[244:247], v186, s[70:71] offset:528
	v_lshlrev_b64 v[158:159], 10, v[156:157]
	v_lshl_add_u64 v[160:161], s[10:11], 0, v[146:147]
	v_lshl_add_u64 v[188:189], v[160:161], 0, v[158:159]
	v_or_b32_e32 v146, 0x100, v146
	v_readlane_b32 s80, v238, 32
	v_readlane_b32 s81, v238, 33
	v_readlane_b32 s82, v238, 34
	v_readlane_b32 s83, v238, 35
	s_mov_b64 s[82:83], s[38:39]
	s_mov_b64 s[80:81], s[36:37]
	v_readlane_b32 s69, v238, 21
	v_readlane_b32 s72, v238, 24
	v_readlane_b32 s73, v238, 25
	v_readlane_b32 s74, v238, 26
	v_readlane_b32 s75, v238, 27
	v_readlane_b32 s76, v238, 28
	v_readlane_b32 s77, v238, 29
	v_readlane_b32 s78, v238, 30
	v_readlane_b32 s79, v238, 31
	s_waitcnt vmcnt(2)
	v_add_f32_e32 v157, v126, v134
	v_add_f32_e32 v168, v127, v135
	v_add_f32_e32 v169, v128, v136
	v_add_f32_e32 v170, v129, v137
	v_add_f32_e32 v171, v122, v130
	v_add_f32_e32 v172, v123, v131
	v_add_f32_e32 v173, v124, v132
	v_add_f32_e32 v174, v125, v133
	v_mul_f32_e32 v157, 0xbfb8aa3b, v157
	v_mul_f32_e32 v168, 0xbfb8aa3b, v168
	v_mul_f32_e32 v169, 0xbfb8aa3b, v169
	v_mul_f32_e32 v170, 0xbfb8aa3b, v170
	v_mul_f32_e32 v171, 0xbfb8aa3b, v171
	v_mul_f32_e32 v172, 0xbfb8aa3b, v172
	v_mul_f32_e32 v173, 0xbfb8aa3b, v173
	v_mul_f32_e32 v174, 0xbfb8aa3b, v174
	v_exp_f32_e32 v157, v157
	v_exp_f32_e32 v168, v168
	v_exp_f32_e32 v169, v169
	v_exp_f32_e32 v170, v170
	v_exp_f32_e32 v171, v171
	v_exp_f32_e32 v172, v172
	v_exp_f32_e32 v173, v173
	v_exp_f32_e32 v174, v174
	v_add_f32_e32 v175, v118, v134
	v_add_f32_e32 v187, v119, v135
	v_add_f32_e32 v190, v120, v136
	v_add_f32_e32 v191, v121, v137
	v_add_f32_e32 v192, v114, v130
	v_add_f32_e32 v193, v115, v131
	v_add_f32_e32 v194, v116, v132
	v_add_f32_e32 v195, v117, v133
	v_add_f32_e32 v157, 1.0, v157
	v_add_f32_e32 v168, 1.0, v168
	v_add_f32_e32 v169, 1.0, v169
	v_add_f32_e32 v170, 1.0, v170
	v_add_f32_e32 v171, 1.0, v171
	v_add_f32_e32 v172, 1.0, v172
	v_add_f32_e32 v173, 1.0, v173
	v_add_f32_e32 v174, 1.0, v174
	v_mul_f32_e32 v175, 0xbfb8aa3b, v175
	v_mul_f32_e32 v187, 0xbfb8aa3b, v187
	v_mul_f32_e32 v190, 0xbfb8aa3b, v190
	v_mul_f32_e32 v191, 0xbfb8aa3b, v191
	v_mul_f32_e32 v192, 0xbfb8aa3b, v192
	v_mul_f32_e32 v193, 0xbfb8aa3b, v193
	v_mul_f32_e32 v194, 0xbfb8aa3b, v194
	v_mul_f32_e32 v195, 0xbfb8aa3b, v195
	v_rcp_f32_e32 v157, v157
	v_rcp_f32_e32 v168, v168
	v_rcp_f32_e32 v169, v169
	v_rcp_f32_e32 v170, v170
	v_rcp_f32_e32 v171, v171
	v_rcp_f32_e32 v172, v172
	v_rcp_f32_e32 v173, v173
	v_rcp_f32_e32 v174, v174
	v_exp_f32_e32 v175, v175
	v_exp_f32_e32 v187, v187
	v_exp_f32_e32 v190, v190
	v_exp_f32_e32 v191, v191
	v_exp_f32_e32 v192, v192
	v_exp_f32_e32 v193, v193
	v_exp_f32_e32 v194, v194
	v_exp_f32_e32 v195, v195
	v_cvt_pk_bf16_f32 v168, v157, v168
	v_cvt_pk_bf16_f32 v169, v169, v170
	v_cvt_pk_bf16_f32 v170, v171, v172
	v_cvt_pk_bf16_f32 v171, v173, v174
	v_add_f32_e32 v175, 1.0, v175
	v_add_f32_e32 v187, 1.0, v187
	v_add_f32_e32 v190, 1.0, v190
	v_add_f32_e32 v191, 1.0, v191
	v_add_f32_e32 v192, 1.0, v192
	v_add_f32_e32 v193, 1.0, v193
	v_add_f32_e32 v194, 1.0, v194
	v_add_f32_e32 v195, 1.0, v195
	global_store_dwordx4 v[188:189], v[168:171], off
	v_rcp_f32_e32 v175, v175
	v_rcp_f32_e32 v187, v187
	v_add_f32_e32 v168, v111, v135
	v_rcp_f32_e32 v190, v190
	v_rcp_f32_e32 v191, v191
	v_rcp_f32_e32 v192, v192
	v_rcp_f32_e32 v193, v193
	v_rcp_f32_e32 v194, v194
	v_rcp_f32_e32 v195, v195
	v_mul_f32_e32 v168, 0xbfb8aa3b, v168
	v_exp_f32_e32 v168, v168
	v_lshlrev_b64 v[170:171], 10, v[166:167]
	v_cvt_pk_bf16_f32 v172, v175, v187
	v_cvt_pk_bf16_f32 v173, v190, v191
	v_cvt_pk_bf16_f32 v174, v192, v193
	v_cvt_pk_bf16_f32 v175, v194, v195
	v_lshl_add_u64 v[166:167], v[160:161], 0, v[170:171]
	global_store_dwordx4 v[166:167], v[172:175], off
	v_add_f32_e32 v166, 1.0, v168
	v_add_f32_e32 v167, v112, v136
	v_add_f32_e32 v168, v113, v137
	v_add_f32_e32 v169, v106, v130
	v_add_f32_e32 v172, v107, v131
	v_add_f32_e32 v173, v108, v132
	v_add_f32_e32 v174, v109, v133
	v_mul_f32_e32 v167, 0xbfb8aa3b, v167
	v_mul_f32_e32 v168, 0xbfb8aa3b, v168
	v_mul_f32_e32 v169, 0xbfb8aa3b, v169
	v_mul_f32_e32 v172, 0xbfb8aa3b, v172
	v_mul_f32_e32 v173, 0xbfb8aa3b, v173
	v_mul_f32_e32 v174, 0xbfb8aa3b, v174
	v_exp_f32_e32 v167, v167
	v_exp_f32_e32 v168, v168
	v_exp_f32_e32 v169, v169
	v_exp_f32_e32 v172, v172
	v_exp_f32_e32 v173, v173
	v_exp_f32_e32 v174, v174
	v_add_f32_e32 v157, v110, v134
	v_mul_f32_e32 v157, 0xbfb8aa3b, v157
	v_add_f32_e32 v167, 1.0, v167
	v_add_f32_e32 v168, 1.0, v168
	v_add_f32_e32 v169, 1.0, v169
	v_add_f32_e32 v172, 1.0, v172
	v_add_f32_e32 v173, 1.0, v173
	v_add_f32_e32 v174, 1.0, v174
	v_exp_f32_e32 v157, v157
	v_rcp_f32_e32 v167, v167
	v_rcp_f32_e32 v168, v168
	v_rcp_f32_e32 v169, v169
	v_rcp_f32_e32 v172, v172
	v_rcp_f32_e32 v173, v173
	v_rcp_f32_e32 v174, v174
	v_add_f32_e32 v157, 1.0, v157
	v_cvt_pk_bf16_f32 v167, v167, v168
	v_cvt_pk_bf16_f32 v168, v169, v172
	v_cvt_pk_bf16_f32 v169, v173, v174
	v_add_f32_e32 v174, v103, v135
	v_rcp_f32_e32 v157, v157
	v_rcp_f32_e32 v166, v166
	v_mul_f32_e32 v174, 0xbfb8aa3b, v174
	v_exp_f32_e32 v174, v174
	v_lshlrev_b64 v[172:173], 10, v[164:165]
	v_cvt_pk_bf16_f32 v166, v157, v166
	v_lshl_add_u64 v[164:165], v[160:161], 0, v[172:173]
	global_store_dwordx4 v[164:165], v[166:169], off
	v_add_f32_e32 v164, 1.0, v174
	v_add_f32_e32 v165, v104, v136
	v_add_f32_e32 v166, v105, v137
	v_add_f32_e32 v167, v98, v130
	v_add_f32_e32 v168, v99, v131
	v_add_f32_e32 v169, v100, v132
	v_add_f32_e32 v174, v101, v133
	v_add_f32_e32 v157, v102, v134
	v_mul_f32_e32 v165, 0xbfb8aa3b, v165
	v_mul_f32_e32 v166, 0xbfb8aa3b, v166
	v_mul_f32_e32 v167, 0xbfb8aa3b, v167
	v_mul_f32_e32 v168, 0xbfb8aa3b, v168
	v_mul_f32_e32 v169, 0xbfb8aa3b, v169
	v_mul_f32_e32 v174, 0xbfb8aa3b, v174
	v_mul_f32_e32 v157, 0xbfb8aa3b, v157
	v_exp_f32_e32 v165, v165
	v_exp_f32_e32 v166, v166
	v_exp_f32_e32 v167, v167
	v_exp_f32_e32 v168, v168
	v_exp_f32_e32 v169, v169
	v_exp_f32_e32 v174, v174
	v_exp_f32_e32 v157, v157
	v_add_f32_e32 v165, 1.0, v165
	v_add_f32_e32 v166, 1.0, v166
	v_add_f32_e32 v167, 1.0, v167
	v_add_f32_e32 v168, 1.0, v168
	v_add_f32_e32 v169, 1.0, v169
	v_add_f32_e32 v174, 1.0, v174
	v_add_f32_e32 v157, 1.0, v157
	v_rcp_f32_e32 v165, v165
	v_rcp_f32_e32 v166, v166
	v_rcp_f32_e32 v167, v167
	v_rcp_f32_e32 v168, v168
	v_rcp_f32_e32 v169, v169
	v_rcp_f32_e32 v174, v174
	v_rcp_f32_e32 v157, v157
	v_rcp_f32_e32 v164, v164
	v_cvt_pk_bf16_f32 v165, v165, v166
	v_cvt_pk_bf16_f32 v166, v167, v168
	v_cvt_pk_bf16_f32 v167, v169, v174
	v_lshlrev_b64 v[174:175], 10, v[162:163]
	v_cvt_pk_bf16_f32 v164, v157, v164
	v_lshl_add_u64 v[162:163], v[160:161], 0, v[174:175]
	v_add_f32_e32 v168, v95, v135
	v_mul_f32_e32 v168, 0xbfb8aa3b, v168
	global_store_dwordx4 v[162:163], v[164:167], off
	v_add_f32_e32 v163, v96, v136
	v_exp_f32_e32 v168, v168
	v_mul_f32_e32 v163, 0xbfb8aa3b, v163
	v_add_f32_e32 v164, v97, v137
	v_exp_f32_e32 v163, v163
	v_mul_f32_e32 v164, 0xbfb8aa3b, v164
	v_exp_f32_e32 v164, v164
	v_add_f32_e32 v162, 1.0, v168
	v_rcp_f32_e32 v165, v162
	v_add_f32_e32 v162, 1.0, v163
	v_add_f32_e32 v163, v90, v130
	v_rcp_f32_e32 v166, v162
	v_add_f32_e32 v162, 1.0, v164
	v_mul_f32_e32 v163, 0xbfb8aa3b, v163
	v_add_f32_e32 v164, v91, v131
	v_exp_f32_e32 v163, v163
	v_mul_f32_e32 v164, 0xbfb8aa3b, v164
	v_exp_f32_e32 v164, v164
	v_rcp_f32_e32 v167, v162
	v_add_f32_e32 v162, 1.0, v163
	v_add_f32_e32 v163, v92, v132
	v_add_f32_e32 v157, v94, v134
	v_rcp_f32_e32 v168, v162
	v_add_f32_e32 v162, 1.0, v164
	v_mul_f32_e32 v163, 0xbfb8aa3b, v163
	v_add_f32_e32 v164, v93, v133
	v_mul_f32_e32 v157, 0xbfb8aa3b, v157
	v_exp_f32_e32 v163, v163
	v_mul_f32_e32 v164, 0xbfb8aa3b, v164
	v_exp_f32_e32 v157, v157
	v_exp_f32_e32 v164, v164
	v_rcp_f32_e32 v169, v162
	v_add_f32_e32 v162, 1.0, v163
	v_add_f32_e32 v157, 1.0, v157
	v_rcp_f32_e32 v187, v162
	v_add_f32_e32 v162, 1.0, v164
	v_rcp_f32_e32 v157, v157
	v_rcp_f32_e32 v188, v162
	v_lshl_add_u64 v[162:163], v[158:159], 0, s[18:19]
	v_lshl_add_u64 v[170:171], s[10:11], 0, v[170:171]
	v_cvt_pk_bf16_f32 v164, v157, v165
	v_cvt_pk_bf16_f32 v165, v166, v167
	v_cvt_pk_bf16_f32 v166, v168, v169
	v_cvt_pk_bf16_f32 v167, v187, v188
	v_lshl_add_u64 v[168:169], v[160:161], 0, v[162:163]
	v_add_f32_e32 v187, v87, v135
	v_mul_f32_e32 v187, 0xbfb8aa3b, v187
	global_store_dwordx4 v[168:169], v[164:167], off
	v_exp_f32_e32 v187, v187
	v_add_f32_e32 v157, v86, v134
	v_add_f32_e32 v165, v88, v136
	v_mul_f32_e32 v165, 0xbfb8aa3b, v165
	v_add_f32_e32 v166, v89, v137
	v_exp_f32_e32 v165, v165
	v_mul_f32_e32 v166, 0xbfb8aa3b, v166
	v_exp_f32_e32 v166, v166
	v_add_f32_e32 v164, 1.0, v187
	v_rcp_f32_e32 v167, v164
	v_add_f32_e32 v164, 1.0, v165
	v_add_f32_e32 v165, v82, v130
	v_rcp_f32_e32 v168, v164
	v_add_f32_e32 v164, 1.0, v166
	v_mul_f32_e32 v165, 0xbfb8aa3b, v165
	v_add_f32_e32 v166, v83, v131
	v_exp_f32_e32 v165, v165
	v_mul_f32_e32 v166, 0xbfb8aa3b, v166
	v_exp_f32_e32 v166, v166
	v_rcp_f32_e32 v169, v164
	v_add_f32_e32 v164, 1.0, v165
	v_add_f32_e32 v165, v84, v132
	v_rcp_f32_e32 v187, v164
	v_add_f32_e32 v164, 1.0, v166
	v_mul_f32_e32 v165, 0xbfb8aa3b, v165
	v_add_f32_e32 v166, v85, v133
	v_mul_f32_e32 v157, 0xbfb8aa3b, v157
	v_exp_f32_e32 v165, v165
	v_mul_f32_e32 v166, 0xbfb8aa3b, v166
	v_exp_f32_e32 v157, v157
	v_exp_f32_e32 v166, v166
	v_rcp_f32_e32 v188, v164
	v_add_f32_e32 v164, 1.0, v165
	v_add_f32_e32 v157, 1.0, v157
	v_rcp_f32_e32 v189, v164
	v_add_f32_e32 v164, 1.0, v166
	v_rcp_f32_e32 v157, v157
	v_rcp_f32_e32 v190, v164
	v_lshl_add_u64 v[164:165], v[158:159], 0, s[20:21]
	v_lshl_add_u64 v[170:171], v[170:171], 0, v[146:147]
	v_cvt_pk_bf16_f32 v166, v157, v167
	v_cvt_pk_bf16_f32 v167, v168, v169
	v_cvt_pk_bf16_f32 v168, v187, v188
	v_cvt_pk_bf16_f32 v169, v189, v190
	v_lshl_add_u64 v[188:189], v[160:161], 0, v[164:165]
	v_add_f32_e32 v187, v79, v135
	v_mul_f32_e32 v187, 0xbfb8aa3b, v187
	global_store_dwordx4 v[188:189], v[166:169], off
	v_exp_f32_e32 v187, v187
	v_add_f32_e32 v157, v78, v134
	v_add_f32_e32 v167, v80, v136
	v_mul_f32_e32 v167, 0xbfb8aa3b, v167
	v_add_f32_e32 v168, v81, v137
	v_exp_f32_e32 v167, v167
	v_mul_f32_e32 v168, 0xbfb8aa3b, v168
	v_exp_f32_e32 v168, v168
	v_add_f32_e32 v166, 1.0, v187
	v_rcp_f32_e32 v169, v166
	v_add_f32_e32 v166, 1.0, v167
	v_add_f32_e32 v167, v74, v130
	v_mul_f32_e32 v157, 0xbfb8aa3b, v157
	v_rcp_f32_e32 v187, v166
	v_add_f32_e32 v166, 1.0, v168
	v_mul_f32_e32 v167, 0xbfb8aa3b, v167
	v_add_f32_e32 v168, v75, v131
	v_exp_f32_e32 v157, v157
	v_exp_f32_e32 v167, v167
	v_mul_f32_e32 v168, 0xbfb8aa3b, v168
	v_exp_f32_e32 v168, v168
	v_add_f32_e32 v130, v62, v130
	v_mul_f32_e32 v130, 0xbfb8aa3b, v130
	v_add_f32_e32 v131, v63, v131
	v_add_f32_e32 v157, 1.0, v157
	v_rcp_f32_e32 v189, v166
	v_add_f32_e32 v166, 1.0, v167
	v_add_f32_e32 v167, v76, v132
	v_exp_f32_e32 v130, v130
	v_mul_f32_e32 v131, 0xbfb8aa3b, v131
	v_rcp_f32_e32 v157, v157
	v_rcp_f32_e32 v190, v166
	v_add_f32_e32 v166, 1.0, v168
	v_mul_f32_e32 v167, 0xbfb8aa3b, v167
	v_add_f32_e32 v168, v77, v133
	v_exp_f32_e32 v131, v131
	v_exp_f32_e32 v167, v167
	v_mul_f32_e32 v168, 0xbfb8aa3b, v168
	v_exp_f32_e32 v168, v168
	v_add_f32_e32 v130, 1.0, v130
	v_cvt_pk_bf16_f32 v188, v157, v169
	v_rcp_f32_e32 v157, v130
	v_add_f32_e32 v130, 1.0, v131
	v_add_f32_e32 v131, v64, v132
	v_rcp_f32_e32 v191, v166
	v_add_f32_e32 v166, 1.0, v167
	v_add_f32_e32 v134, v70, v134
	v_add_f32_e32 v135, v71, v135
	v_add_f32_e32 v136, v72, v136
	v_add_f32_e32 v137, v73, v137
	v_mul_f32_e32 v131, 0xbfb8aa3b, v131
	v_add_f32_e32 v132, v65, v133
	v_rcp_f32_e32 v192, v166
	v_add_f32_e32 v166, 1.0, v168
	v_mul_f32_e32 v134, 0xbfb8aa3b, v134
	v_mul_f32_e32 v135, 0xbfb8aa3b, v135
	v_mul_f32_e32 v136, 0xbfb8aa3b, v136
	v_mul_f32_e32 v137, 0xbfb8aa3b, v137
	v_exp_f32_e32 v131, v131
	v_mul_f32_e32 v132, 0xbfb8aa3b, v132
	v_rcp_f32_e32 v168, v166
	v_exp_f32_e32 v134, v134
	v_exp_f32_e32 v135, v135
	v_exp_f32_e32 v136, v136
	v_exp_f32_e32 v137, v137
	v_exp_f32_e32 v132, v132
	v_lshl_add_u64 v[166:167], v[158:159], 0, s[22:23]
	v_rcp_f32_e32 v133, v130
	v_add_f32_e32 v130, 1.0, v131
	v_cvt_pk_bf16_f32 v189, v187, v189
	v_cvt_pk_bf16_f32 v190, v190, v191
	v_cvt_pk_bf16_f32 v191, v192, v168
	v_lshl_add_u64 v[168:169], v[160:161], 0, v[166:167]
	v_add_f32_e32 v134, 1.0, v134
	v_add_f32_e32 v135, 1.0, v135
	v_add_f32_e32 v136, 1.0, v136
	v_add_f32_e32 v137, 1.0, v137
	v_rcp_f32_e32 v187, v130
	v_add_f32_e32 v130, 1.0, v132
	global_store_dwordx4 v[168:169], v[188:191], off
	v_rcp_f32_e32 v134, v134
	v_rcp_f32_e32 v135, v135
	v_rcp_f32_e32 v136, v136
	v_rcp_f32_e32 v137, v137
	v_rcp_f32_e32 v188, v130
	v_lshl_add_u64 v[168:169], v[158:159], 0, s[24:25]
	v_cvt_pk_bf16_f32 v130, v134, v135
	v_cvt_pk_bf16_f32 v131, v136, v137
	v_cvt_pk_bf16_f32 v132, v157, v133
	v_cvt_pk_bf16_f32 v133, v187, v188
	v_lshl_add_u64 v[134:135], v[160:161], 0, v[168:169]
	global_store_dwordx4 v[134:135], v[130:133], off
	s_nop 3
	s_waitcnt vmcnt(8)
	v_mov_b64_e32 v[134:135], v[240:241]
	v_mov_b64_e32 v[136:137], v[242:243]
	v_mov_b64_e32 v[130:131], v[244:245]
	v_mov_b64_e32 v[132:133], v[246:247]
	v_lshl_add_u64 v[158:159], s[10:11], 0, v[158:159]
	v_lshl_add_u64 v[158:159], v[158:159], 0, v[146:147]
	v_lshl_add_u64 v[162:163], s[10:11], 0, v[162:163]
	v_lshl_add_u64 v[162:163], v[162:163], 0, v[146:147]
	v_add_f32_e32 v186, v69, v137
	v_mul_f32_e32 v186, 0xbfb8aa3b, v186
	v_add_f32_e32 v187, v58, v130
	v_exp_f32_e32 v186, v186
	v_mul_f32_e32 v187, 0xbfb8aa3b, v187
	v_add_f32_e32 v188, v59, v131
	v_exp_f32_e32 v187, v187
	v_mul_f32_e32 v188, 0xbfb8aa3b, v188
	v_add_f32_e32 v157, v66, v134
	v_add_f32_e32 v160, v67, v135
	v_exp_f32_e32 v188, v188
	v_mul_f32_e32 v157, 0xbfb8aa3b, v157
	v_mul_f32_e32 v160, 0xbfb8aa3b, v160
	v_exp_f32_e32 v157, v157
	v_exp_f32_e32 v160, v160
	v_add_f32_e32 v186, 1.0, v186
	v_rcp_f32_e32 v189, v186
	v_add_f32_e32 v186, 1.0, v187
	v_add_f32_e32 v187, v60, v132
	v_rcp_f32_e32 v190, v186
	v_add_f32_e32 v186, 1.0, v188
	v_mul_f32_e32 v187, 0xbfb8aa3b, v187
	v_add_f32_e32 v188, v61, v133
	v_add_f32_e32 v161, v68, v136
	v_exp_f32_e32 v187, v187
	v_mul_f32_e32 v188, 0xbfb8aa3b, v188
	v_add_f32_e32 v157, 1.0, v157
	v_add_f32_e32 v160, 1.0, v160
	v_mul_f32_e32 v161, 0xbfb8aa3b, v161
	v_exp_f32_e32 v188, v188
	v_rcp_f32_e32 v157, v157
	v_exp_f32_e32 v161, v161
	v_rcp_f32_e32 v160, v160
	v_rcp_f32_e32 v191, v186
	v_add_f32_e32 v186, 1.0, v187
	v_rcp_f32_e32 v192, v186
	v_add_f32_e32 v186, 1.0, v188
	v_add_f32_e32 v161, 1.0, v161
	v_rcp_f32_e32 v193, v186
	v_cvt_pk_bf16_f32 v186, v157, v160
	v_add_f32_e32 v160, v55, v135
	v_rcp_f32_e32 v161, v161
	v_mul_f32_e32 v160, 0xbfb8aa3b, v160
	v_exp_f32_e32 v160, v160
	v_cvt_pk_bf16_f32 v188, v190, v191
	v_cvt_pk_bf16_f32 v187, v161, v189
	v_cvt_pk_bf16_f32 v189, v192, v193
	global_store_dwordx4 v[158:159], v[186:189], off
	v_add_f32_e32 v158, 1.0, v160
	v_add_f32_e32 v159, v56, v136
	v_add_f32_e32 v160, v57, v137
	v_add_f32_e32 v161, v50, v130
	v_add_f32_e32 v186, v51, v131
	v_mul_f32_e32 v159, 0xbfb8aa3b, v159
	v_mul_f32_e32 v160, 0xbfb8aa3b, v160
	v_mul_f32_e32 v161, 0xbfb8aa3b, v161
	v_mul_f32_e32 v186, 0xbfb8aa3b, v186
	v_exp_f32_e32 v159, v159
	v_exp_f32_e32 v160, v160
	v_exp_f32_e32 v161, v161
	v_exp_f32_e32 v186, v186
	v_add_f32_e32 v157, v54, v134
	v_add_f32_e32 v187, v52, v132
	v_add_f32_e32 v188, v53, v133
	v_mul_f32_e32 v157, 0xbfb8aa3b, v157
	v_add_f32_e32 v159, 1.0, v159
	v_add_f32_e32 v160, 1.0, v160
	v_add_f32_e32 v161, 1.0, v161
	v_add_f32_e32 v186, 1.0, v186
	v_mul_f32_e32 v187, 0xbfb8aa3b, v187
	v_mul_f32_e32 v188, 0xbfb8aa3b, v188
	v_exp_f32_e32 v157, v157
	v_rcp_f32_e32 v159, v159
	v_rcp_f32_e32 v160, v160
	v_rcp_f32_e32 v161, v161
	v_exp_f32_e32 v187, v187
	v_exp_f32_e32 v188, v188
	v_rcp_f32_e32 v186, v186
	v_add_f32_e32 v157, 1.0, v157
	v_add_f32_e32 v187, 1.0, v187
	v_add_f32_e32 v188, 1.0, v188
	v_cvt_pk_bf16_f32 v159, v159, v160
	v_cvt_pk_bf16_f32 v160, v161, v186
	v_add_f32_e32 v186, v47, v135
	v_rcp_f32_e32 v157, v157
	v_rcp_f32_e32 v158, v158
	v_rcp_f32_e32 v187, v187
	v_rcp_f32_e32 v188, v188
	v_mul_f32_e32 v186, 0xbfb8aa3b, v186
	v_exp_f32_e32 v186, v186
	v_cvt_pk_bf16_f32 v158, v157, v158
	v_cvt_pk_bf16_f32 v161, v187, v188
	global_store_dwordx4 v[170:171], v[158:161], off
	v_add_f32_e32 v170, v43, v131
	v_add_f32_e32 v171, v44, v132
	v_add_f32_e32 v158, 1.0, v186
	v_add_f32_e32 v159, v48, v136
	v_add_f32_e32 v160, v49, v137
	v_add_f32_e32 v161, v42, v130
	v_add_f32_e32 v186, v45, v133
	v_mul_f32_e32 v159, 0xbfb8aa3b, v159
	v_mul_f32_e32 v160, 0xbfb8aa3b, v160
	v_mul_f32_e32 v161, 0xbfb8aa3b, v161
	v_mul_f32_e32 v170, 0xbfb8aa3b, v170
	v_mul_f32_e32 v171, 0xbfb8aa3b, v171
	v_mul_f32_e32 v186, 0xbfb8aa3b, v186
	v_exp_f32_e32 v159, v159
	v_exp_f32_e32 v160, v160
	v_exp_f32_e32 v161, v161
	v_exp_f32_e32 v170, v170
	v_exp_f32_e32 v171, v171
	v_exp_f32_e32 v186, v186
	v_add_f32_e32 v157, v46, v134
	v_mul_f32_e32 v157, 0xbfb8aa3b, v157
	v_add_f32_e32 v159, 1.0, v159
	v_add_f32_e32 v160, 1.0, v160
	v_add_f32_e32 v161, 1.0, v161
	v_add_f32_e32 v170, 1.0, v170
	v_add_f32_e32 v171, 1.0, v171
	v_add_f32_e32 v186, 1.0, v186
	v_exp_f32_e32 v157, v157
	v_rcp_f32_e32 v159, v159
	v_rcp_f32_e32 v160, v160
	v_rcp_f32_e32 v161, v161
	v_rcp_f32_e32 v170, v170
	v_rcp_f32_e32 v171, v171
	v_rcp_f32_e32 v186, v186
	v_add_f32_e32 v157, 1.0, v157
	v_cvt_pk_bf16_f32 v159, v159, v160
	v_cvt_pk_bf16_f32 v160, v161, v170
	v_cvt_pk_bf16_f32 v161, v171, v186
	v_lshl_add_u64 v[170:171], s[10:11], 0, v[172:173]
	v_add_f32_e32 v172, v39, v135
	v_rcp_f32_e32 v157, v157
	v_rcp_f32_e32 v158, v158
	v_mul_f32_e32 v172, 0xbfb8aa3b, v172
	v_exp_f32_e32 v172, v172
	v_lshl_add_u64 v[170:171], v[170:171], 0, v[146:147]
	v_cvt_pk_bf16_f32 v158, v157, v158
	global_store_dwordx4 v[170:171], v[158:161], off
	v_add_f32_e32 v170, v35, v131
	v_add_f32_e32 v171, v36, v132
	v_add_f32_e32 v158, 1.0, v172
	v_add_f32_e32 v159, v40, v136
	v_add_f32_e32 v160, v41, v137
	v_add_f32_e32 v161, v34, v130
	v_add_f32_e32 v172, v37, v133
	v_add_f32_e32 v157, v38, v134
	v_mul_f32_e32 v159, 0xbfb8aa3b, v159
	v_mul_f32_e32 v160, 0xbfb8aa3b, v160
	v_mul_f32_e32 v161, 0xbfb8aa3b, v161
	v_mul_f32_e32 v170, 0xbfb8aa3b, v170
	v_mul_f32_e32 v171, 0xbfb8aa3b, v171
	v_mul_f32_e32 v172, 0xbfb8aa3b, v172
	v_mul_f32_e32 v157, 0xbfb8aa3b, v157
	v_exp_f32_e32 v159, v159
	v_exp_f32_e32 v160, v160
	v_exp_f32_e32 v161, v161
	v_exp_f32_e32 v170, v170
	v_exp_f32_e32 v171, v171
	v_exp_f32_e32 v172, v172
	v_exp_f32_e32 v157, v157
	v_add_f32_e32 v159, 1.0, v159
	v_add_f32_e32 v160, 1.0, v160
	v_add_f32_e32 v161, 1.0, v161
	v_add_f32_e32 v170, 1.0, v170
	v_add_f32_e32 v171, 1.0, v171
	v_add_f32_e32 v172, 1.0, v172
	v_add_f32_e32 v157, 1.0, v157
	v_rcp_f32_e32 v159, v159
	v_rcp_f32_e32 v160, v160
	v_rcp_f32_e32 v161, v161
	v_rcp_f32_e32 v170, v170
	v_rcp_f32_e32 v171, v171
	v_rcp_f32_e32 v172, v172
	v_rcp_f32_e32 v157, v157
	v_rcp_f32_e32 v158, v158
	v_cvt_pk_bf16_f32 v159, v159, v160
	v_cvt_pk_bf16_f32 v160, v161, v170
	v_cvt_pk_bf16_f32 v161, v171, v172
	v_lshl_add_u64 v[170:171], s[10:11], 0, v[174:175]
	v_cvt_pk_bf16_f32 v158, v157, v158
	v_lshl_add_u64 v[170:171], v[170:171], 0, v[146:147]
	v_add_f32_e32 v172, v31, v135
	v_mul_f32_e32 v172, 0xbfb8aa3b, v172
	global_store_dwordx4 v[170:171], v[158:161], off
	v_add_f32_e32 v170, v27, v131
	v_exp_f32_e32 v172, v172
	v_add_f32_e32 v159, v32, v136
	v_add_f32_e32 v160, v33, v137
	v_add_f32_e32 v161, v26, v130
	v_mul_f32_e32 v159, 0xbfb8aa3b, v159
	v_mul_f32_e32 v160, 0xbfb8aa3b, v160
	v_mul_f32_e32 v161, 0xbfb8aa3b, v161
	v_mul_f32_e32 v170, 0xbfb8aa3b, v170
	v_exp_f32_e32 v159, v159
	v_exp_f32_e32 v160, v160
	v_exp_f32_e32 v161, v161
	v_exp_f32_e32 v170, v170
	v_add_f32_e32 v157, v30, v134
	v_add_f32_e32 v158, 1.0, v172
	v_add_f32_e32 v171, v28, v132
	v_add_f32_e32 v172, v29, v133
	v_mul_f32_e32 v157, 0xbfb8aa3b, v157
	v_add_f32_e32 v159, 1.0, v159
	v_add_f32_e32 v160, 1.0, v160
	v_add_f32_e32 v161, 1.0, v161
	v_add_f32_e32 v170, 1.0, v170
	v_mul_f32_e32 v171, 0xbfb8aa3b, v171
	v_mul_f32_e32 v172, 0xbfb8aa3b, v172
	v_exp_f32_e32 v157, v157
	v_rcp_f32_e32 v159, v159
	v_rcp_f32_e32 v160, v160
	v_rcp_f32_e32 v161, v161
	v_exp_f32_e32 v171, v171
	v_exp_f32_e32 v172, v172
	v_rcp_f32_e32 v170, v170
	v_add_f32_e32 v157, 1.0, v157
	v_add_f32_e32 v171, 1.0, v171
	v_add_f32_e32 v172, 1.0, v172
	v_cvt_pk_bf16_f32 v159, v159, v160
	v_cvt_pk_bf16_f32 v160, v161, v170
	v_add_f32_e32 v170, v23, v135
	v_rcp_f32_e32 v157, v157
	v_rcp_f32_e32 v158, v158
	v_rcp_f32_e32 v171, v171
	v_rcp_f32_e32 v172, v172
	v_mul_f32_e32 v170, 0xbfb8aa3b, v170
	v_exp_f32_e32 v170, v170
	v_cvt_pk_bf16_f32 v158, v157, v158
	v_cvt_pk_bf16_f32 v161, v171, v172
	global_store_dwordx4 v[162:163], v[158:161], off
	v_add_f32_e32 v162, v19, v131
	v_add_f32_e32 v163, v20, v132
	v_add_f32_e32 v158, 1.0, v170
	v_add_f32_e32 v159, v24, v136
	v_add_f32_e32 v160, v25, v137
	v_add_f32_e32 v161, v18, v130
	v_add_f32_e32 v170, v21, v133
	v_add_f32_e32 v157, v22, v134
	v_mul_f32_e32 v159, 0xbfb8aa3b, v159
	v_mul_f32_e32 v160, 0xbfb8aa3b, v160
	v_mul_f32_e32 v161, 0xbfb8aa3b, v161
	v_mul_f32_e32 v162, 0xbfb8aa3b, v162
	v_mul_f32_e32 v163, 0xbfb8aa3b, v163
	v_mul_f32_e32 v170, 0xbfb8aa3b, v170
	v_mul_f32_e32 v157, 0xbfb8aa3b, v157
	v_exp_f32_e32 v159, v159
	v_exp_f32_e32 v160, v160
	v_exp_f32_e32 v161, v161
	v_exp_f32_e32 v162, v162
	v_exp_f32_e32 v163, v163
	v_exp_f32_e32 v170, v170
	v_exp_f32_e32 v157, v157
	v_add_f32_e32 v159, 1.0, v159
	v_add_f32_e32 v160, 1.0, v160
	v_add_f32_e32 v161, 1.0, v161
	v_add_f32_e32 v162, 1.0, v162
	v_add_f32_e32 v163, 1.0, v163
	v_add_f32_e32 v170, 1.0, v170
	v_add_f32_e32 v157, 1.0, v157
	v_rcp_f32_e32 v159, v159
	v_rcp_f32_e32 v160, v160
	v_rcp_f32_e32 v161, v161
	v_rcp_f32_e32 v162, v162
	v_rcp_f32_e32 v163, v163
	v_rcp_f32_e32 v170, v170
	v_rcp_f32_e32 v157, v157
	v_rcp_f32_e32 v158, v158
	v_cvt_pk_bf16_f32 v159, v159, v160
	v_cvt_pk_bf16_f32 v160, v161, v162
	v_cvt_pk_bf16_f32 v161, v163, v170
	v_lshl_add_u64 v[162:163], s[10:11], 0, v[164:165]
	v_add_f32_e32 v164, v15, v135
	v_cvt_pk_bf16_f32 v158, v157, v158
	v_add_f32_e32 v157, v14, v134
	v_mul_f32_e32 v164, 0xbfb8aa3b, v164
	v_mul_f32_e32 v157, 0xbfb8aa3b, v157
	v_exp_f32_e32 v164, v164
	v_exp_f32_e32 v157, v157
	v_lshl_add_u64 v[162:163], v[162:163], 0, v[146:147]
	global_store_dwordx4 v[162:163], v[158:161], off
	v_add_f32_e32 v162, v11, v131
	v_add_f32_e32 v163, v12, v132
	v_add_f32_e32 v161, v10, v130
	v_add_f32_e32 v130, v2, v130
	v_add_f32_e32 v158, 1.0, v164
	v_add_f32_e32 v159, v16, v136
	v_add_f32_e32 v160, v17, v137
	v_add_f32_e32 v164, v13, v133
	v_mul_f32_e32 v130, 0xbfb8aa3b, v130
	v_add_f32_e32 v131, v3, v131
	v_add_f32_e32 v157, 1.0, v157
	v_mul_f32_e32 v159, 0xbfb8aa3b, v159
	v_mul_f32_e32 v160, 0xbfb8aa3b, v160
	v_mul_f32_e32 v161, 0xbfb8aa3b, v161
	v_mul_f32_e32 v162, 0xbfb8aa3b, v162
	v_mul_f32_e32 v163, 0xbfb8aa3b, v163
	v_mul_f32_e32 v164, 0xbfb8aa3b, v164
	v_exp_f32_e32 v130, v130
	v_mul_f32_e32 v131, 0xbfb8aa3b, v131
	v_rcp_f32_e32 v157, v157
	v_exp_f32_e32 v159, v159
	v_exp_f32_e32 v160, v160
	v_rcp_f32_e32 v158, v158
	v_exp_f32_e32 v161, v161
	v_exp_f32_e32 v162, v162
	v_exp_f32_e32 v163, v163
	v_exp_f32_e32 v164, v164
	v_exp_f32_e32 v131, v131
	v_add_f32_e32 v130, 1.0, v130
	v_add_f32_e32 v159, 1.0, v159
	v_add_f32_e32 v160, 1.0, v160
	v_add_f32_e32 v161, 1.0, v161
	v_add_f32_e32 v162, 1.0, v162
	v_add_f32_e32 v163, 1.0, v163
	v_add_f32_e32 v164, 1.0, v164
	v_cvt_pk_bf16_f32 v158, v157, v158
	v_add_f32_e32 v134, v6, v134
	v_add_f32_e32 v135, v7, v135
	v_rcp_f32_e32 v157, v130
	v_add_f32_e32 v130, 1.0, v131
	v_add_f32_e32 v131, v4, v132
	v_rcp_f32_e32 v159, v159
	v_rcp_f32_e32 v160, v160
	v_rcp_f32_e32 v161, v161
	v_rcp_f32_e32 v162, v162
	v_rcp_f32_e32 v163, v163
	v_rcp_f32_e32 v164, v164
	v_mul_f32_e32 v134, 0xbfb8aa3b, v134
	v_mul_f32_e32 v135, 0xbfb8aa3b, v135
	v_add_f32_e32 v136, v8, v136
	v_add_f32_e32 v137, v9, v137
	v_mul_f32_e32 v131, 0xbfb8aa3b, v131
	v_add_f32_e32 v132, v5, v133
	v_exp_f32_e32 v134, v134
	v_exp_f32_e32 v135, v135
	v_mul_f32_e32 v136, 0xbfb8aa3b, v136
	v_mul_f32_e32 v137, 0xbfb8aa3b, v137
	v_exp_f32_e32 v131, v131
	v_mul_f32_e32 v132, 0xbfb8aa3b, v132
	v_exp_f32_e32 v136, v136
	v_exp_f32_e32 v137, v137
	v_exp_f32_e32 v132, v132
	v_cvt_pk_bf16_f32 v159, v159, v160
	v_cvt_pk_bf16_f32 v160, v161, v162
	v_cvt_pk_bf16_f32 v161, v163, v164
	v_lshl_add_u64 v[162:163], s[10:11], 0, v[166:167]
	v_lshl_add_u64 v[162:163], v[162:163], 0, v[146:147]
	v_add_f32_e32 v134, 1.0, v134
	v_add_f32_e32 v135, 1.0, v135
	v_rcp_f32_e32 v133, v130
	v_add_f32_e32 v130, 1.0, v131
	global_store_dwordx4 v[162:163], v[158:161], off
	v_rcp_f32_e32 v134, v134
	v_rcp_f32_e32 v135, v135
	v_add_f32_e32 v136, 1.0, v136
	v_add_f32_e32 v137, 1.0, v137
	v_rcp_f32_e32 v158, v130
	v_add_f32_e32 v130, 1.0, v132
	v_rcp_f32_e32 v136, v136
	v_rcp_f32_e32 v137, v137
	v_rcp_f32_e32 v159, v130
	v_cvt_pk_bf16_f32 v130, v134, v135
	v_lshl_add_u64 v[134:135], s[10:11], 0, v[168:169]
	v_cvt_pk_bf16_f32 v131, v136, v137
	v_cvt_pk_bf16_f32 v132, v157, v133
	v_cvt_pk_bf16_f32 v133, v158, v159
	v_lshl_add_u64 v[134:135], v[134:135], 0, v[146:147]
	global_store_dwordx4 v[134:135], v[130:133], off

.LBB0_1356:
	v_or_b32_e32 v4, s24, v187
	v_ashrrev_i32_e32 v5, 31, v4
	v_lshlrev_b64 v[4:5], 1, v[4:5]
	v_or_b32_e32 v156, 16, v176
	v_lshl_add_u64 v[134:135], v[178:179], 0, v[4:5]
	v_ashrrev_i32_e32 v157, 31, v156
	global_load_dwordx4 v[136:139], v[134:135], off offset:2048
	global_load_dwordx4 v[140:143], v[134:135], off offset:2304
	v_lshlrev_b64 v[134:135], 12, v[156:157]
	v_lshl_add_u64 v[134:135], s[62:63], 0, v[134:135]
	v_lshl_add_u64 v[134:135], v[134:135], 0, v[4:5]
	global_load_dwordx4 v[144:147], v[134:135], off offset:2048
	global_load_dwordx4 v[148:151], v[134:135], off offset:2304
	v_or_b32_e32 v194, 32, v176
	v_lshlrev_b64 v[152:153], 11, v[176:177]
	v_ashrrev_i32_e32 v195, 31, v194
	v_lshl_add_u64 v[178:179], s[8:9], 0, v[152:153]
	v_lshlrev_b64 v[152:153], 12, v[194:195]
	v_lshl_add_u64 v[152:153], s[62:63], 0, v[152:153]
	v_lshl_add_u64 v[182:183], v[152:153], 0, v[4:5]
	global_load_dwordx4 v[152:155], v[182:183], off offset:2048
	v_or_b32_e32 v134, 48, v176
	v_ashrrev_i32_e32 v135, 31, v134
	v_lshlrev_b64 v[180:181], 12, v[134:135]
	v_lshl_add_u64 v[180:181], s[62:63], 0, v[180:181]
	v_lshl_add_u64 v[190:191], v[180:181], 0, v[4:5]
	v_lshl_add_u64 v[196:197], v[178:179], 0, v[4:5]
	global_load_dwordx4 v[178:181], v[182:183], off offset:2304
	s_nop 0
	global_load_dwordx4 v[182:185], v[190:191], off offset:2048
	s_nop 0
	global_load_dwordx4 v[190:193], v[190:191], off offset:2304
	v_add_u32_e32 v240, 0x80, v176
	v_ashrrev_i32_e32 v241, 31, v240
	v_lshlrev_b64 v[242:243], 12, v[240:241]
	v_lshl_add_u64 v[242:243], s[62:63], 0, v[242:243]
	v_lshl_add_u64 v[242:243], v[4:5], 0, v[242:243]
	global_load_dwordx4 v[206:209], v[242:243], off offset:2048
	global_load_dwordx4 v[210:213], v[242:243], off offset:2304
	v_add_u32_e32 v240, 0x90, v176
	v_ashrrev_i32_e32 v241, 31, v240
	v_lshlrev_b64 v[242:243], 12, v[240:241]
	v_lshl_add_u64 v[242:243], s[62:63], 0, v[242:243]
	v_lshl_add_u64 v[242:243], v[4:5], 0, v[242:243]
	global_load_dwordx4 v[214:217], v[242:243], off offset:2048
	global_load_dwordx4 v[218:221], v[242:243], off offset:2304
	v_add_u32_e32 v240, 0xa0, v176
	v_ashrrev_i32_e32 v241, 31, v240
	v_lshlrev_b64 v[242:243], 12, v[240:241]
	v_lshl_add_u64 v[242:243], s[62:63], 0, v[242:243]
	v_lshl_add_u64 v[242:243], v[4:5], 0, v[242:243]
	global_load_dwordx4 v[222:225], v[242:243], off offset:2048
	global_load_dwordx4 v[226:229], v[242:243], off offset:2304
	v_add_u32_e32 v240, 0xb0, v176
	v_ashrrev_i32_e32 v241, 31, v240
	v_lshlrev_b64 v[242:243], 12, v[240:241]
	v_lshl_add_u64 v[242:243], s[62:63], 0, v[242:243]
	v_lshl_add_u64 v[242:243], v[4:5], 0, v[242:243]
	global_load_dwordx4 v[230:233], v[242:243], off offset:2048
	global_load_dwordx4 v[234:237], v[242:243], off offset:2304
	v_lshlrev_b64 v[156:157], 11, v[156:157]
	v_lshl_add_u64 v[156:157], s[8:9], 0, v[156:157]
	v_lshl_add_u64 v[156:157], v[156:157], 0, v[4:5]
	s_andn2_b64 vcc, exec, s[0:1]
	s_mov_b64 s[0:1], -1
	s_waitcnt vmcnt(8)
	v_lshlrev_b32_e32 v200, 16, v138
	v_and_b32_e32 v201, 0xffff0000, v138
	v_lshlrev_b32_e32 v138, 16, v139
	v_and_b32_e32 v139, 0xffff0000, v139
	v_lshlrev_b32_e32 v202, 16, v140
	v_and_b32_e32 v203, 0xffff0000, v140
	v_lshlrev_b32_e32 v140, 16, v141
	v_and_b32_e32 v141, 0xffff0000, v141
	v_lshlrev_b32_e32 v204, 16, v142
	v_and_b32_e32 v205, 0xffff0000, v142
	v_lshlrev_b32_e32 v142, 16, v143
	v_and_b32_e32 v143, 0xffff0000, v143
	v_lshlrev_b32_e32 v198, 16, v136
	v_and_b32_e32 v199, 0xffff0000, v136
	v_lshlrev_b32_e32 v136, 16, v137
	v_and_b32_e32 v137, 0xffff0000, v137
	v_pk_mul_f32 v[126:127], v[126:127], v[200:201]
	v_pk_mul_f32 v[128:129], v[128:129], v[138:139]
	v_pk_mul_f32 v[124:125], v[124:125], v[140:141]
	v_pk_mul_f32 v[138:139], v[120:121], v[142:143]
	v_lshlrev_b32_e32 v140, 16, v144
	v_and_b32_e32 v141, 0xffff0000, v144
	v_lshlrev_b32_e32 v142, 16, v145
	v_and_b32_e32 v143, 0xffff0000, v145
	v_lshlrev_b32_e32 v144, 16, v146
	v_and_b32_e32 v145, 0xffff0000, v146
	v_lshlrev_b32_e32 v146, 16, v147
	v_and_b32_e32 v147, 0xffff0000, v147
	v_pk_mul_f32 v[130:131], v[130:131], v[198:199]
	v_pk_mul_f32 v[132:133], v[132:133], v[136:137]
	v_cvt_pk_bf16_f32 v120, v126, v127
	v_cvt_pk_bf16_f32 v121, v128, v129
	v_pk_mul_f32 v[114:115], v[114:115], v[140:141]
	v_pk_mul_f32 v[116:117], v[116:117], v[142:143]
	v_pk_mul_f32 v[126:127], v[110:111], v[144:145]
	v_pk_mul_f32 v[128:129], v[112:113], v[146:147]
	v_pk_mul_f32 v[122:123], v[122:123], v[202:203]
	v_pk_mul_f32 v[136:137], v[118:119], v[204:205]
	v_cvt_pk_bf16_f32 v118, v130, v131
	v_cvt_pk_bf16_f32 v119, v132, v133
	v_cvt_pk_bf16_f32 v110, v114, v115
	v_cvt_pk_bf16_f32 v111, v116, v117
	v_cvt_pk_bf16_f32 v112, v126, v127
	v_cvt_pk_bf16_f32 v113, v128, v129
	v_cvt_pk_bf16_f32 v122, v122, v123
	v_cvt_pk_bf16_f32 v123, v124, v125
	v_cvt_pk_bf16_f32 v124, v136, v137
	v_cvt_pk_bf16_f32 v125, v138, v139
	global_store_dwordx4 v[196:197], v[118:121], off
	global_store_dwordx4 v[196:197], v[122:125], off offset:256
	global_store_dwordx4 v[156:157], v[110:113], off
	v_lshlrev_b32_e32 v198, 16, v148
	v_and_b32_e32 v199, 0xffff0000, v148
	v_lshlrev_b32_e32 v110, 16, v150
	v_and_b32_e32 v111, 0xffff0000, v150
	v_lshlrev_b32_e32 v148, 16, v149
	v_and_b32_e32 v149, 0xffff0000, v149
	v_pk_mul_f32 v[110:111], v[102:103], v[110:111]
	v_lshlrev_b32_e32 v102, 16, v151
	v_and_b32_e32 v103, 0xffff0000, v151
	v_pk_mul_f32 v[106:107], v[106:107], v[198:199]
	v_pk_mul_f32 v[108:109], v[108:109], v[148:149]
	v_pk_mul_f32 v[112:113], v[104:105], v[102:103]
	v_cvt_pk_bf16_f32 v102, v106, v107
	v_cvt_pk_bf16_f32 v103, v108, v109
	v_cvt_pk_bf16_f32 v104, v110, v111
	v_cvt_pk_bf16_f32 v105, v112, v113
	global_store_dwordx4 v[156:157], v[102:105], off offset:256
	v_add_u32_e32 v108, 0xb0, v176
	v_ashrrev_i32_e32 v109, 31, v108
	v_lshlrev_b32_e32 v104, 16, v152
	v_and_b32_e32 v105, 0xffff0000, v152
	v_pk_mul_f32 v[98:99], v[98:99], v[104:105]
	v_lshlrev_b32_e32 v104, 16, v153
	v_and_b32_e32 v105, 0xffff0000, v153
	v_pk_mul_f32 v[100:101], v[100:101], v[104:105]
	v_lshlrev_b32_e32 v104, 16, v154
	v_and_b32_e32 v105, 0xffff0000, v154
	v_lshlrev_b64 v[102:103], 11, v[194:195]
	v_pk_mul_f32 v[104:105], v[94:95], v[104:105]
	v_lshlrev_b32_e32 v94, 16, v155
	v_and_b32_e32 v95, 0xffff0000, v155
	v_pk_mul_f32 v[106:107], v[96:97], v[94:95]
	v_cvt_pk_bf16_f32 v94, v98, v99
	v_lshl_add_u64 v[98:99], s[8:9], 0, v[102:103]
	v_cvt_pk_bf16_f32 v95, v100, v101
	v_cvt_pk_bf16_f32 v96, v104, v105
	v_cvt_pk_bf16_f32 v97, v106, v107
	v_lshl_add_u64 v[98:99], v[98:99], 0, v[4:5]
	global_store_dwordx4 v[98:99], v[94:97], off
	v_add_u32_e32 v102, 0x80, v176
	v_ashrrev_i32_e32 v103, 31, v102
	v_lshlrev_b32_e32 v94, 16, v178
	v_and_b32_e32 v95, 0xffff0000, v178
	v_pk_mul_f32 v[90:91], v[90:91], v[94:95]
	v_lshlrev_b32_e32 v94, 16, v179
	v_and_b32_e32 v95, 0xffff0000, v179
	v_pk_mul_f32 v[92:93], v[92:93], v[94:95]
	v_lshlrev_b32_e32 v94, 16, v180
	v_and_b32_e32 v95, 0xffff0000, v180
	v_pk_mul_f32 v[94:95], v[86:87], v[94:95]
	v_lshlrev_b32_e32 v86, 16, v181
	v_and_b32_e32 v87, 0xffff0000, v181
	v_pk_mul_f32 v[96:97], v[88:89], v[86:87]
	v_cvt_pk_bf16_f32 v86, v90, v91
	v_cvt_pk_bf16_f32 v87, v92, v93
	v_cvt_pk_bf16_f32 v88, v94, v95
	v_cvt_pk_bf16_f32 v89, v96, v97
	global_store_dwordx4 v[98:99], v[86:89], off offset:256
	v_add_u32_e32 v104, 0x90, v176
	v_ashrrev_i32_e32 v105, 31, v104
	v_lshlrev_b32_e32 v88, 16, v182
	v_and_b32_e32 v89, 0xffff0000, v182
	v_pk_mul_f32 v[82:83], v[82:83], v[88:89]
	v_lshlrev_b32_e32 v88, 16, v183
	v_and_b32_e32 v89, 0xffff0000, v183
	v_pk_mul_f32 v[84:85], v[84:85], v[88:89]
	v_lshlrev_b32_e32 v88, 16, v184
	v_and_b32_e32 v89, 0xffff0000, v184
	v_lshlrev_b64 v[86:87], 11, v[134:135]
	v_pk_mul_f32 v[88:89], v[78:79], v[88:89]
	v_lshlrev_b32_e32 v78, 16, v185
	v_and_b32_e32 v79, 0xffff0000, v185
	v_pk_mul_f32 v[90:91], v[80:81], v[78:79]
	v_cvt_pk_bf16_f32 v78, v82, v83
	v_lshl_add_u64 v[82:83], s[8:9], 0, v[86:87]
	v_cvt_pk_bf16_f32 v79, v84, v85
	v_cvt_pk_bf16_f32 v80, v88, v89
	v_cvt_pk_bf16_f32 v81, v90, v91
	v_lshl_add_u64 v[82:83], v[82:83], 0, v[4:5]
	global_store_dwordx4 v[82:83], v[78:81], off
	v_add_u32_e32 v106, 0xa0, v176
	v_ashrrev_i32_e32 v107, 31, v106
	v_lshlrev_b32_e32 v78, 16, v190
	v_and_b32_e32 v79, 0xffff0000, v190
	v_pk_mul_f32 v[74:75], v[74:75], v[78:79]
	v_lshlrev_b32_e32 v78, 16, v191
	v_and_b32_e32 v79, 0xffff0000, v191
	v_pk_mul_f32 v[76:77], v[76:77], v[78:79]
	v_lshlrev_b32_e32 v78, 16, v192
	v_and_b32_e32 v79, 0xffff0000, v192
	v_pk_mul_f32 v[78:79], v[70:71], v[78:79]
	v_lshlrev_b32_e32 v70, 16, v193
	v_and_b32_e32 v71, 0xffff0000, v193
	v_pk_mul_f32 v[80:81], v[72:73], v[70:71]
	v_cvt_pk_bf16_f32 v70, v74, v75
	v_cvt_pk_bf16_f32 v71, v76, v77
	v_cvt_pk_bf16_f32 v72, v78, v79
	v_cvt_pk_bf16_f32 v73, v80, v81
	global_store_dwordx4 v[82:83], v[70:73], off offset:256
	s_nop 1
	v_lshlrev_b64 v[70:71], 12, v[102:103]
	v_lshl_add_u64 v[70:71], s[62:63], 0, v[70:71]
	v_lshl_add_u64 v[70:71], v[70:71], 0, v[4:5]
	v_lshlrev_b64 v[70:71], 12, v[104:105]
	v_lshl_add_u64 v[70:71], s[62:63], 0, v[70:71]
	v_lshl_add_u64 v[70:71], v[70:71], 0, v[4:5]
	v_lshlrev_b64 v[70:71], 12, v[106:107]
	v_lshl_add_u64 v[70:71], s[62:63], 0, v[70:71]
	v_lshl_add_u64 v[70:71], v[70:71], 0, v[4:5]
	v_lshlrev_b64 v[70:71], 12, v[108:109]
	v_lshl_add_u64 v[70:71], s[62:63], 0, v[70:71]
	v_lshl_add_u64 v[70:71], v[70:71], 0, v[4:5]
	s_nop 0
	s_waitcnt vmcnt(8)
	v_mov_b64_e32 v[74:75], v[206:207]
	v_mov_b64_e32 v[76:77], v[208:209]
	v_mov_b64_e32 v[78:79], v[210:211]
	v_mov_b64_e32 v[80:81], v[212:213]
	v_mov_b64_e32 v[82:83], v[214:215]
	v_mov_b64_e32 v[84:85], v[216:217]
	v_mov_b64_e32 v[86:87], v[218:219]
	v_mov_b64_e32 v[88:89], v[220:221]
	v_mov_b64_e32 v[90:91], v[222:223]
	v_mov_b64_e32 v[92:93], v[224:225]
	v_mov_b64_e32 v[94:95], v[226:227]
	v_mov_b64_e32 v[96:97], v[228:229]
	v_mov_b64_e32 v[98:99], v[230:231]
	v_mov_b64_e32 v[100:101], v[232:233]
	v_mov_b64_e32 v[70:71], v[234:235]
	v_mov_b64_e32 v[72:73], v[236:237]
	v_lshlrev_b64 v[102:103], 11, v[102:103]
	v_lshlrev_b32_e32 v110, 16, v74
	v_and_b32_e32 v111, 0xffff0000, v74
	v_lshlrev_b32_e32 v74, 16, v75
	v_and_b32_e32 v75, 0xffff0000, v75
	v_pk_mul_f32 v[68:69], v[68:69], v[74:75]
	v_lshlrev_b32_e32 v74, 16, v76
	v_and_b32_e32 v75, 0xffff0000, v76
	v_pk_mul_f32 v[66:67], v[66:67], v[110:111]
	v_pk_mul_f32 v[74:75], v[62:63], v[74:75]
	v_lshlrev_b32_e32 v62, 16, v77
	v_and_b32_e32 v63, 0xffff0000, v77
	v_pk_mul_f32 v[76:77], v[64:65], v[62:63]
	v_cvt_pk_bf16_f32 v62, v66, v67
	v_lshl_add_u64 v[66:67], s[8:9], 0, v[102:103]
	v_cvt_pk_bf16_f32 v63, v68, v69
	v_cvt_pk_bf16_f32 v64, v74, v75
	v_cvt_pk_bf16_f32 v65, v76, v77
	v_lshl_add_u64 v[66:67], v[66:67], 0, v[4:5]
	global_store_dwordx4 v[66:67], v[62:65], off
	s_nop 0
	v_lshlrev_b32_e32 v62, 16, v78
	v_and_b32_e32 v63, 0xffff0000, v78
	v_pk_mul_f32 v[58:59], v[58:59], v[62:63]
	v_lshlrev_b32_e32 v62, 16, v79
	v_and_b32_e32 v63, 0xffff0000, v79
	v_pk_mul_f32 v[60:61], v[60:61], v[62:63]
	v_lshlrev_b32_e32 v62, 16, v80
	v_and_b32_e32 v63, 0xffff0000, v80
	v_pk_mul_f32 v[62:63], v[54:55], v[62:63]
	v_lshlrev_b32_e32 v54, 16, v81
	v_and_b32_e32 v55, 0xffff0000, v81
	v_pk_mul_f32 v[64:65], v[56:57], v[54:55]
	v_cvt_pk_bf16_f32 v54, v58, v59
	v_cvt_pk_bf16_f32 v55, v60, v61
	v_cvt_pk_bf16_f32 v56, v62, v63
	v_cvt_pk_bf16_f32 v57, v64, v65
	global_store_dwordx4 v[66:67], v[54:57], off offset:256
	s_nop 0
	v_lshlrev_b32_e32 v56, 16, v82
	v_and_b32_e32 v57, 0xffff0000, v82
	v_pk_mul_f32 v[50:51], v[50:51], v[56:57]
	v_lshlrev_b32_e32 v56, 16, v83
	v_and_b32_e32 v57, 0xffff0000, v83
	v_pk_mul_f32 v[52:53], v[52:53], v[56:57]
	v_lshlrev_b32_e32 v56, 16, v84
	v_and_b32_e32 v57, 0xffff0000, v84
	v_lshlrev_b64 v[54:55], 11, v[104:105]
	v_pk_mul_f32 v[56:57], v[46:47], v[56:57]
	v_lshlrev_b32_e32 v46, 16, v85
	v_and_b32_e32 v47, 0xffff0000, v85
	v_pk_mul_f32 v[58:59], v[48:49], v[46:47]
	v_cvt_pk_bf16_f32 v46, v50, v51
	v_lshl_add_u64 v[50:51], s[8:9], 0, v[54:55]
	v_cvt_pk_bf16_f32 v47, v52, v53
	v_cvt_pk_bf16_f32 v48, v56, v57
	v_cvt_pk_bf16_f32 v49, v58, v59
	v_lshl_add_u64 v[50:51], v[50:51], 0, v[4:5]
	global_store_dwordx4 v[50:51], v[46:49], off
	s_nop 0
	v_lshlrev_b32_e32 v46, 16, v86
	v_and_b32_e32 v47, 0xffff0000, v86
	v_pk_mul_f32 v[42:43], v[42:43], v[46:47]
	v_lshlrev_b32_e32 v46, 16, v87
	v_and_b32_e32 v47, 0xffff0000, v87
	v_pk_mul_f32 v[44:45], v[44:45], v[46:47]
	v_lshlrev_b32_e32 v46, 16, v88
	v_and_b32_e32 v47, 0xffff0000, v88
	v_pk_mul_f32 v[46:47], v[38:39], v[46:47]
	v_lshlrev_b32_e32 v38, 16, v89
	v_and_b32_e32 v39, 0xffff0000, v89
	v_pk_mul_f32 v[48:49], v[40:41], v[38:39]
	v_cvt_pk_bf16_f32 v38, v42, v43
	v_cvt_pk_bf16_f32 v39, v44, v45
	v_cvt_pk_bf16_f32 v40, v46, v47
	v_cvt_pk_bf16_f32 v41, v48, v49
	global_store_dwordx4 v[50:51], v[38:41], off offset:256
	s_nop 0
	v_lshlrev_b32_e32 v40, 16, v90
	v_and_b32_e32 v41, 0xffff0000, v90
	v_pk_mul_f32 v[34:35], v[34:35], v[40:41]
	v_lshlrev_b32_e32 v40, 16, v91
	v_and_b32_e32 v41, 0xffff0000, v91
	v_pk_mul_f32 v[36:37], v[36:37], v[40:41]
	v_lshlrev_b32_e32 v40, 16, v92
	v_and_b32_e32 v41, 0xffff0000, v92
	v_lshlrev_b64 v[38:39], 11, v[106:107]
	v_pk_mul_f32 v[40:41], v[30:31], v[40:41]
	v_lshlrev_b32_e32 v30, 16, v93
	v_and_b32_e32 v31, 0xffff0000, v93
	v_pk_mul_f32 v[42:43], v[32:33], v[30:31]
	v_cvt_pk_bf16_f32 v30, v34, v35
	v_lshl_add_u64 v[34:35], s[8:9], 0, v[38:39]
	v_cvt_pk_bf16_f32 v31, v36, v37
	v_cvt_pk_bf16_f32 v32, v40, v41
	v_cvt_pk_bf16_f32 v33, v42, v43
	v_lshl_add_u64 v[34:35], v[34:35], 0, v[4:5]
	global_store_dwordx4 v[34:35], v[30:33], off
	s_nop 0
	v_lshlrev_b32_e32 v30, 16, v94
	v_and_b32_e32 v31, 0xffff0000, v94
	v_pk_mul_f32 v[26:27], v[26:27], v[30:31]
	v_lshlrev_b32_e32 v30, 16, v95
	v_and_b32_e32 v31, 0xffff0000, v95
	v_pk_mul_f32 v[28:29], v[28:29], v[30:31]
	v_lshlrev_b32_e32 v30, 16, v96
	v_and_b32_e32 v31, 0xffff0000, v96
	v_pk_mul_f32 v[30:31], v[22:23], v[30:31]
	v_lshlrev_b32_e32 v22, 16, v97
	v_and_b32_e32 v23, 0xffff0000, v97
	v_pk_mul_f32 v[32:33], v[24:25], v[22:23]
	v_cvt_pk_bf16_f32 v22, v26, v27
	v_cvt_pk_bf16_f32 v23, v28, v29
	v_cvt_pk_bf16_f32 v24, v30, v31
	v_cvt_pk_bf16_f32 v25, v32, v33
	global_store_dwordx4 v[34:35], v[22:25], off offset:256
	s_nop 0
	v_lshlrev_b32_e32 v24, 16, v98
	v_and_b32_e32 v25, 0xffff0000, v98
	v_pk_mul_f32 v[18:19], v[18:19], v[24:25]
	v_lshlrev_b32_e32 v24, 16, v99
	v_and_b32_e32 v25, 0xffff0000, v99
	v_pk_mul_f32 v[20:21], v[20:21], v[24:25]
	v_lshlrev_b32_e32 v24, 16, v100
	v_and_b32_e32 v25, 0xffff0000, v100
	v_lshlrev_b64 v[22:23], 11, v[108:109]
	v_pk_mul_f32 v[24:25], v[14:15], v[24:25]
	v_lshlrev_b32_e32 v14, 16, v101
	v_and_b32_e32 v15, 0xffff0000, v101
	v_pk_mul_f32 v[26:27], v[16:17], v[14:15]
	v_cvt_pk_bf16_f32 v14, v18, v19
	v_lshl_add_u64 v[18:19], s[8:9], 0, v[22:23]
	v_lshl_add_u64 v[18:19], v[18:19], 0, v[4:5]
	v_lshlrev_b32_e32 v4, 16, v70
	v_and_b32_e32 v5, 0xffff0000, v70
	v_pk_mul_f32 v[4:5], v[10:11], v[4:5]
	v_lshlrev_b32_e32 v10, 16, v71
	v_and_b32_e32 v11, 0xffff0000, v71
	v_pk_mul_f32 v[10:11], v[12:13], v[10:11]
	v_lshlrev_b32_e32 v12, 16, v72
	v_and_b32_e32 v13, 0xffff0000, v72
	v_pk_mul_f32 v[6:7], v[6:7], v[12:13]
	v_lshlrev_b32_e32 v12, 16, v73
	v_and_b32_e32 v13, 0xffff0000, v73
	v_pk_mul_f32 v[8:9], v[8:9], v[12:13]
	v_cvt_pk_bf16_f32 v15, v20, v21
	v_cvt_pk_bf16_f32 v16, v24, v25
	v_cvt_pk_bf16_f32 v17, v26, v27
	v_cvt_pk_bf16_f32 v4, v4, v5
	v_cvt_pk_bf16_f32 v5, v10, v11
	v_cvt_pk_bf16_f32 v6, v6, v7
	v_cvt_pk_bf16_f32 v7, v8, v9
	global_store_dwordx4 v[18:19], v[14:17], off
	global_store_dwordx4 v[18:19], v[4:7], off offset:256
	s_cbranch_vccnz .LBB0_1343
	s_andn2_b64 vcc, exec, s[6:7]
	s_cbranch_vccnz .LBB0_1342
	s_barrier
	s_branch .LBB0_1342
